# GEMM main loops: LDS-DMA loads use SGPR base + VGPR offset addressing, 8 of 16 64-bit VALU address adds per K iteration removed
# speedup vs baseline: 1.0030x; 1.0030x over previous
.LBB0_48:
	s_ashr_i32 s13, s12, 31
	v_cmp_lt_i64_e32 vcc, s[16:17], v[162:163]
	s_lshl_b64 s[16:17], s[12:13], 19
	s_add_u32 s16, s8, s16
	s_addc_u32 s17, s9, s17
	s_and_b64 s[18:19], vcc, exec
	s_cselect_b32 s13, s17, s23
	s_cselect_b32 s67, s16, s22
	s_ashr_i32 s11, s10, 31
	s_lshl_b64 s[18:19], s[10:11], 19
	s_add_u32 s18, s31, s18
	s_addc_u32 s19, s35, s19
	s_and_b64 s[62:63], vcc, exec
	s_cselect_b32 s11, s19, s59
	s_cselect_b32 s68, s18, s58
	s_add_u32 s22, s22, 0x40080
	s_addc_u32 s23, s23, 0
	s_add_u32 s69, s58, 0x100
	s_addc_u32 s72, s59, 0
	s_mov_b32 s73, -2
	s_waitcnt lgkmcnt(0)
	s_add_u32 s2, s22, 0xfffc0080
	s_addc_u32 s15, s23, -1
	s_add_i32 s74, 0, 0x10000
	v_add_u32_e32 v150, s74, v153
	ds_read_b128 v[128:131], v150
	ds_read_b128 v[132:135], v150 offset:1024
	ds_read_b128 v[136:139], v150 offset:2048
	ds_read_b128 v[166:169], v150 offset:3072
	s_cmp_eq_u32 s73, 12
	s_cselect_b32 s63, s13, s15
	s_cselect_b32 s62, s67, s2
	s_cselect_b32 s59, s11, s72
	s_cselect_b32 s58, s68, s69
	s_add_i32 m0, s21, 0xc000
	ds_read_b128 v[170:173], v155
	ds_read_b128 v[174:177], v155 offset:1024
	ds_read_b128 v[178:181], v155 offset:2048
	ds_read_b128 v[182:185], v155 offset:3072
	ds_read_b128 v[186:189], v155 offset:4096
	ds_read_b128 v[214:217], v155 offset:5120
	ds_read_b128 v[218:221], v155 offset:6144
	ds_read_b128 v[222:225], v155 offset:7168
	global_load_lds_dwordx4 v146, s[22:23]
	s_add_i32 m0, s21, 0xe000
	s_nop 0
	global_load_lds_dwordx4 v148, s[22:23]
	s_waitcnt lgkmcnt(8)
	s_barrier
	s_waitcnt lgkmcnt(0)
	s_setprio 1
	s_waitcnt lgkmcnt(0)
	v_mfma_f32_16x16x32_bf16 v[124:127], v[128:131], v[170:173], 0
	v_mfma_f32_16x16x32_bf16 v[120:123], v[136:139], v[170:173], 0
	v_mfma_f32_16x16x32_bf16 v[108:111], v[128:131], v[178:181], 0
	v_mfma_f32_16x16x32_bf16 v[104:107], v[136:139], v[178:181], 0
	v_mfma_f32_16x16x32_bf16 v[92:95], v[128:131], v[186:189], 0
	v_mfma_f32_16x16x32_bf16 v[88:91], v[136:139], v[186:189], 0
	v_mfma_f32_16x16x32_bf16 v[76:79], v[128:131], v[218:221], 0
	v_mfma_f32_16x16x32_bf16 v[72:75], v[136:139], v[218:221], 0
	v_mfma_f32_16x16x32_bf16 v[124:127], v[132:135], v[174:177], v[124:127]
	v_mfma_f32_16x16x32_bf16 v[120:123], v[166:169], v[174:177], v[120:123]
	v_mfma_f32_16x16x32_bf16 v[108:111], v[132:135], v[182:185], v[108:111]
	v_mfma_f32_16x16x32_bf16 v[104:107], v[166:169], v[182:185], v[104:107]
	v_mfma_f32_16x16x32_bf16 v[92:95], v[132:135], v[214:217], v[92:95]
	v_mfma_f32_16x16x32_bf16 v[88:91], v[166:169], v[214:217], v[88:91]
	v_mfma_f32_16x16x32_bf16 v[76:79], v[132:135], v[222:225], v[76:79]
	v_mfma_f32_16x16x32_bf16 v[72:75], v[166:169], v[222:225], v[72:75]
	s_setprio 0
	s_barrier
	s_add_i32 s2, 0, 0x14000
	v_add_u32_e32 v150, s2, v153
	s_add_i32 s15, s74, s39
	ds_read_b128 v[226:229], v150
	ds_read_b128 v[230:233], v150 offset:1024
	ds_read_b128 v[234:237], v150 offset:2048
	ds_read_b128 v[238:241], v150 offset:3072
	v_lshl_add_u64 v[150:151], s[58:59], 0, v[158:159]
	s_mov_b32 m0, s15
	v_lshl_add_u64 v[190:191], s[58:59], 0, v[144:145]
	global_load_lds_dwordx4 v158, s[58:59]
	s_add_i32 m0, s15, 0x2000
	s_nop 0
	global_load_lds_dwordx4 v144, s[58:59]
	s_barrier
	s_waitcnt lgkmcnt(0)
	s_setprio 1
	s_waitcnt lgkmcnt(0)
	v_mfma_f32_16x16x32_bf16 v[116:119], v[226:229], v[170:173], 0
	v_mfma_f32_16x16x32_bf16 v[112:115], v[234:237], v[170:173], 0
	v_mfma_f32_16x16x32_bf16 v[100:103], v[226:229], v[178:181], 0
	v_mfma_f32_16x16x32_bf16 v[96:99], v[234:237], v[178:181], 0
	v_mfma_f32_16x16x32_bf16 v[84:87], v[226:229], v[186:189], 0
	v_mfma_f32_16x16x32_bf16 v[80:83], v[234:237], v[186:189], 0
	v_mfma_f32_16x16x32_bf16 v[68:71], v[226:229], v[218:221], 0
	v_mfma_f32_16x16x32_bf16 v[64:67], v[234:237], v[218:221], 0
	v_mfma_f32_16x16x32_bf16 v[116:119], v[230:233], v[174:177], v[116:119]
	v_mfma_f32_16x16x32_bf16 v[112:115], v[238:241], v[174:177], v[112:115]
	v_mfma_f32_16x16x32_bf16 v[100:103], v[230:233], v[182:185], v[100:103]
	v_mfma_f32_16x16x32_bf16 v[96:99], v[238:241], v[182:185], v[96:99]
	v_mfma_f32_16x16x32_bf16 v[84:87], v[230:233], v[214:217], v[84:87]
	v_mfma_f32_16x16x32_bf16 v[80:83], v[238:241], v[214:217], v[80:83]
	v_mfma_f32_16x16x32_bf16 v[68:71], v[230:233], v[222:225], v[68:71]
	v_mfma_f32_16x16x32_bf16 v[64:67], v[238:241], v[222:225], v[64:67]
	s_setprio 0
	s_mov_b32 m0, s21
	v_lshl_add_u64 v[202:203], s[62:63], 0, v[140:141]
	s_barrier
	ds_read_b128 v[170:173], v155 offset:16384
	ds_read_b128 v[174:177], v155 offset:17408
	ds_read_b128 v[178:181], v155 offset:18432
	ds_read_b128 v[182:185], v155 offset:19456
	ds_read_b128 v[186:189], v155 offset:20480
	ds_read_b128 v[214:217], v155 offset:21504
	ds_read_b128 v[218:221], v155 offset:22528
	ds_read_b128 v[222:225], v155 offset:23552
	global_load_lds_dwordx4 v140, s[62:63]
	v_lshl_add_u64 v[204:205], s[62:63], 0, v[142:143]
	s_mov_b32 m0, s43
	s_nop 0
	global_load_lds_dwordx4 v142, s[62:63]
	s_barrier
	s_waitcnt lgkmcnt(0)
	s_setprio 1
	s_waitcnt lgkmcnt(0)
	v_mfma_f32_16x16x32_bf16 v[60:63], v[128:131], v[170:173], 0
	v_mfma_f32_16x16x32_bf16 v[56:59], v[136:139], v[170:173], 0
	v_mfma_f32_16x16x32_bf16 v[44:47], v[128:131], v[178:181], 0
	v_mfma_f32_16x16x32_bf16 v[40:43], v[136:139], v[178:181], 0
	v_mfma_f32_16x16x32_bf16 v[28:31], v[128:131], v[186:189], 0
	v_mfma_f32_16x16x32_bf16 v[24:27], v[136:139], v[186:189], 0
	v_mfma_f32_16x16x32_bf16 v[12:15], v[128:131], v[218:221], 0
	v_mfma_f32_16x16x32_bf16 v[8:11], v[136:139], v[218:221], 0
	v_mfma_f32_16x16x32_bf16 v[60:63], v[132:135], v[174:177], v[60:63]
	v_mfma_f32_16x16x32_bf16 v[56:59], v[166:169], v[174:177], v[56:59]
	v_mfma_f32_16x16x32_bf16 v[44:47], v[132:135], v[182:185], v[44:47]
	v_mfma_f32_16x16x32_bf16 v[40:43], v[166:169], v[182:185], v[40:43]
	v_mfma_f32_16x16x32_bf16 v[28:31], v[132:135], v[214:217], v[28:31]
	v_mfma_f32_16x16x32_bf16 v[24:27], v[166:169], v[214:217], v[24:27]
	v_mfma_f32_16x16x32_bf16 v[12:15], v[132:135], v[222:225], v[12:15]
	v_mfma_f32_16x16x32_bf16 v[8:11], v[166:169], v[222:225], v[8:11]
	s_setprio 0
	s_barrier
	s_add_u32 s74, s58, 0x40000
	s_addc_u32 s75, s59, 0
	s_add_i32 s2, s2, s39
	s_mov_b32 m0, s2
	s_nop 0
	global_load_lds_dwordx4 v158, s[74:75]
	s_add_i32 m0, s2, 0x2000
	s_nop 0
	global_load_lds_dwordx4 v144, s[74:75]
	s_waitcnt vmcnt(6)
	s_barrier
	s_setprio 1
	v_mfma_f32_16x16x32_bf16 v[52:55], v[226:229], v[170:173], 0
	v_mfma_f32_16x16x32_bf16 v[48:51], v[234:237], v[170:173], 0
	v_mfma_f32_16x16x32_bf16 v[36:39], v[226:229], v[178:181], 0
	v_mfma_f32_16x16x32_bf16 v[32:35], v[234:237], v[178:181], 0
	v_mfma_f32_16x16x32_bf16 v[20:23], v[226:229], v[186:189], 0
	v_mfma_f32_16x16x32_bf16 v[16:19], v[234:237], v[186:189], 0
	v_mfma_f32_16x16x32_bf16 v[4:7], v[226:229], v[218:221], 0
	v_mfma_f32_16x16x32_bf16 v[0:3], v[234:237], v[218:221], 0
	v_mfma_f32_16x16x32_bf16 v[52:55], v[230:233], v[174:177], v[52:55]
	v_mfma_f32_16x16x32_bf16 v[48:51], v[238:241], v[174:177], v[48:51]
	v_mfma_f32_16x16x32_bf16 v[36:39], v[230:233], v[182:185], v[36:39]
	v_mfma_f32_16x16x32_bf16 v[32:35], v[238:241], v[182:185], v[32:35]
	v_mfma_f32_16x16x32_bf16 v[20:23], v[230:233], v[214:217], v[20:23]
	v_mfma_f32_16x16x32_bf16 v[16:19], v[238:241], v[214:217], v[16:19]
	v_mfma_f32_16x16x32_bf16 v[4:7], v[230:233], v[222:225], v[4:7]
	v_mfma_f32_16x16x32_bf16 v[0:3], v[238:241], v[222:225], v[0:3]
	s_setprio 0
	s_add_i32 s2, 0, 0x18000
	v_add_u32_e32 v165, s2, v153
	s_barrier
	ds_read_b128 v[128:131], v165
	ds_read_b128 v[132:135], v165 offset:1024
	ds_read_b128 v[136:139], v165 offset:2048
	ds_read_b128 v[166:169], v165 offset:3072
	s_add_u32 s62, s62, 0x40000
	s_addc_u32 s63, s63, 0
	s_mov_b32 m0, s47
	ds_read_b128 v[170:173], v155 offset:32768
	ds_read_b128 v[174:177], v155 offset:33792
	ds_read_b128 v[178:181], v155 offset:34816
	ds_read_b128 v[182:185], v155 offset:35840
	ds_read_b128 v[186:189], v155 offset:36864
	ds_read_b128 v[214:217], v155 offset:37888
	ds_read_b128 v[218:221], v155 offset:38912
	ds_read_b128 v[222:225], v155 offset:39936
	global_load_lds_dwordx4 v140, s[62:63]
	s_mov_b32 m0, s48
	s_nop 0
	global_load_lds_dwordx4 v142, s[62:63]
	s_waitcnt lgkmcnt(8)
	s_barrier
	s_waitcnt lgkmcnt(0)
	s_setprio 1
	s_waitcnt lgkmcnt(0)
	v_mfma_f32_16x16x32_bf16 v[124:127], v[128:131], v[170:173], v[124:127]
	v_mfma_f32_16x16x32_bf16 v[120:123], v[136:139], v[170:173], v[120:123]
	v_mfma_f32_16x16x32_bf16 v[108:111], v[128:131], v[178:181], v[108:111]
	v_mfma_f32_16x16x32_bf16 v[104:107], v[136:139], v[178:181], v[104:107]
	v_mfma_f32_16x16x32_bf16 v[92:95], v[128:131], v[186:189], v[92:95]
	v_mfma_f32_16x16x32_bf16 v[88:91], v[136:139], v[186:189], v[88:91]
	v_mfma_f32_16x16x32_bf16 v[76:79], v[128:131], v[218:221], v[76:79]
	v_mfma_f32_16x16x32_bf16 v[72:75], v[136:139], v[218:221], v[72:75]
	v_mfma_f32_16x16x32_bf16 v[124:127], v[132:135], v[174:177], v[124:127]
	v_mfma_f32_16x16x32_bf16 v[120:123], v[166:169], v[174:177], v[120:123]
	v_mfma_f32_16x16x32_bf16 v[108:111], v[132:135], v[182:185], v[108:111]
	v_mfma_f32_16x16x32_bf16 v[104:107], v[166:169], v[182:185], v[104:107]
	v_mfma_f32_16x16x32_bf16 v[92:95], v[132:135], v[214:217], v[92:95]
	v_mfma_f32_16x16x32_bf16 v[88:91], v[166:169], v[214:217], v[88:91]
	v_mfma_f32_16x16x32_bf16 v[76:79], v[132:135], v[222:225], v[76:79]
	v_mfma_f32_16x16x32_bf16 v[72:75], v[166:169], v[222:225], v[72:75]
	s_setprio 0
	s_barrier
	s_add_i32 s15, 0, 0x1c000
	s_add_i32 s2, s2, s39
	v_add_u32_e32 v165, s15, v153
	v_lshl_add_u64 v[150:151], v[150:151], 0, s[70:71]
	s_mov_b32 m0, s2
	ds_read_b128 v[226:229], v165
	ds_read_b128 v[230:233], v165 offset:1024
	ds_read_b128 v[234:237], v165 offset:2048
	ds_read_b128 v[238:241], v165 offset:3072
	global_load_lds_dwordx4 v[150:151], off
	v_lshl_add_u64 v[150:151], v[190:191], 0, s[70:71]
	s_add_i32 m0, s2, 0x2000
	s_nop 0
	global_load_lds_dwordx4 v[150:151], off
	s_barrier
	s_waitcnt lgkmcnt(0)
	s_setprio 1
	s_waitcnt lgkmcnt(0)
	v_mfma_f32_16x16x32_bf16 v[116:119], v[226:229], v[170:173], v[116:119]
	v_mfma_f32_16x16x32_bf16 v[112:115], v[234:237], v[170:173], v[112:115]
	v_mfma_f32_16x16x32_bf16 v[100:103], v[226:229], v[178:181], v[100:103]
	v_mfma_f32_16x16x32_bf16 v[96:99], v[234:237], v[178:181], v[96:99]
	v_mfma_f32_16x16x32_bf16 v[84:87], v[226:229], v[186:189], v[84:87]
	v_mfma_f32_16x16x32_bf16 v[80:83], v[234:237], v[186:189], v[80:83]
	v_mfma_f32_16x16x32_bf16 v[68:71], v[226:229], v[218:221], v[68:71]
	v_mfma_f32_16x16x32_bf16 v[64:67], v[234:237], v[218:221], v[64:67]
	v_mfma_f32_16x16x32_bf16 v[116:119], v[230:233], v[174:177], v[116:119]
	v_mfma_f32_16x16x32_bf16 v[112:115], v[238:241], v[174:177], v[112:115]
	v_mfma_f32_16x16x32_bf16 v[100:103], v[230:233], v[182:185], v[100:103]
	v_mfma_f32_16x16x32_bf16 v[96:99], v[238:241], v[182:185], v[96:99]
	v_mfma_f32_16x16x32_bf16 v[84:87], v[230:233], v[214:217], v[84:87]
	v_mfma_f32_16x16x32_bf16 v[80:83], v[238:241], v[214:217], v[80:83]
	v_mfma_f32_16x16x32_bf16 v[68:71], v[230:233], v[222:225], v[68:71]
	v_mfma_f32_16x16x32_bf16 v[64:67], v[238:241], v[222:225], v[64:67]
	s_setprio 0
	s_mov_b32 m0, s50
	v_lshl_add_u64 v[150:151], v[202:203], 0, s[70:71]
	s_barrier
	ds_read_b128 v[170:173], v155 offset:49152
	ds_read_b128 v[174:177], v155 offset:50176
	ds_read_b128 v[178:181], v155 offset:51200
	ds_read_b128 v[182:185], v155 offset:52224
	ds_read_b128 v[186:189], v155 offset:53248
	ds_read_b128 v[214:217], v155 offset:54272
	ds_read_b128 v[218:221], v155 offset:55296
	ds_read_b128 v[222:225], v155 offset:56320
	global_load_lds_dwordx4 v[150:151], off
	v_lshl_add_u64 v[150:151], v[204:205], 0, s[70:71]
	s_mov_b32 m0, s51
	s_nop 0
	global_load_lds_dwordx4 v[150:151], off
	s_barrier
	s_waitcnt lgkmcnt(0)
	s_setprio 1
	s_waitcnt lgkmcnt(0)
	v_mfma_f32_16x16x32_bf16 v[60:63], v[128:131], v[170:173], v[60:63]
	v_mfma_f32_16x16x32_bf16 v[56:59], v[136:139], v[170:173], v[56:59]
	v_mfma_f32_16x16x32_bf16 v[44:47], v[128:131], v[178:181], v[44:47]
	v_mfma_f32_16x16x32_bf16 v[40:43], v[136:139], v[178:181], v[40:43]
	v_mfma_f32_16x16x32_bf16 v[28:31], v[128:131], v[186:189], v[28:31]
	v_mfma_f32_16x16x32_bf16 v[24:27], v[136:139], v[186:189], v[24:27]
	v_mfma_f32_16x16x32_bf16 v[12:15], v[128:131], v[218:221], v[12:15]
	v_mfma_f32_16x16x32_bf16 v[8:11], v[136:139], v[218:221], v[8:11]
	v_mfma_f32_16x16x32_bf16 v[60:63], v[132:135], v[174:177], v[60:63]
	v_mfma_f32_16x16x32_bf16 v[56:59], v[166:169], v[174:177], v[56:59]
	v_mfma_f32_16x16x32_bf16 v[44:47], v[132:135], v[182:185], v[44:47]
	v_mfma_f32_16x16x32_bf16 v[40:43], v[166:169], v[182:185], v[40:43]
	v_mfma_f32_16x16x32_bf16 v[28:31], v[132:135], v[214:217], v[28:31]
	v_mfma_f32_16x16x32_bf16 v[24:27], v[166:169], v[214:217], v[24:27]
	v_mfma_f32_16x16x32_bf16 v[12:15], v[132:135], v[222:225], v[12:15]
	v_mfma_f32_16x16x32_bf16 v[8:11], v[166:169], v[222:225], v[8:11]
	s_setprio 0
	s_barrier
	s_add_u32 s58, s58, 0x40080
	s_addc_u32 s59, s59, 0
	s_add_i32 s2, s15, s39
	s_mov_b32 m0, s2
	s_nop 0
	global_load_lds_dwordx4 v158, s[58:59]
	s_add_i32 m0, s2, 0x2000
	s_nop 0
	global_load_lds_dwordx4 v144, s[58:59]
	s_waitcnt vmcnt(6)
	s_barrier
	s_setprio 1
	v_mfma_f32_16x16x32_bf16 v[52:55], v[226:229], v[170:173], v[52:55]
	v_mfma_f32_16x16x32_bf16 v[48:51], v[234:237], v[170:173], v[48:51]
	v_mfma_f32_16x16x32_bf16 v[36:39], v[226:229], v[178:181], v[36:39]
	v_mfma_f32_16x16x32_bf16 v[32:35], v[234:237], v[178:181], v[32:35]
	v_mfma_f32_16x16x32_bf16 v[20:23], v[226:229], v[186:189], v[20:23]
	v_mfma_f32_16x16x32_bf16 v[16:19], v[234:237], v[186:189], v[16:19]
	v_mfma_f32_16x16x32_bf16 v[4:7], v[226:229], v[218:221], v[4:7]
	v_mfma_f32_16x16x32_bf16 v[0:3], v[234:237], v[218:221], v[0:3]
	v_mfma_f32_16x16x32_bf16 v[52:55], v[230:233], v[174:177], v[52:55]
	v_mfma_f32_16x16x32_bf16 v[48:51], v[238:241], v[174:177], v[48:51]
	v_mfma_f32_16x16x32_bf16 v[36:39], v[230:233], v[182:185], v[36:39]
	v_mfma_f32_16x16x32_bf16 v[32:35], v[238:241], v[182:185], v[32:35]
	v_mfma_f32_16x16x32_bf16 v[20:23], v[230:233], v[214:217], v[20:23]
	v_mfma_f32_16x16x32_bf16 v[16:19], v[238:241], v[214:217], v[16:19]
	v_mfma_f32_16x16x32_bf16 v[4:7], v[230:233], v[222:225], v[4:7]
	v_mfma_f32_16x16x32_bf16 v[0:3], v[238:241], v[222:225], v[0:3]
	s_setprio 0
	s_add_i32 s73, s73, 2
	s_add_u32 s22, s22, 0x100
	s_addc_u32 s23, s23, 0
	s_add_u32 s69, s69, 0x100
	s_addc_u32 s72, s72, 0
	s_cmp_gt_u32 s73, 13
	s_barrier
	s_cbranch_scc1 .Lzp_exit0
.LBB0_49:
	s_add_u32 s2, s22, 0xfffc0080
	s_addc_u32 s15, s23, -1
	s_add_i32 s74, 0, 0x10000
	v_add_u32_e32 v150, s74, v153
	ds_read_b128 v[128:131], v150
	ds_read_b128 v[132:135], v150 offset:1024
	ds_read_b128 v[136:139], v150 offset:2048
	ds_read_b128 v[166:169], v150 offset:3072
	s_cmp_eq_u32 s73, 12
	s_cselect_b32 s63, s13, s15
	s_cselect_b32 s62, s67, s2
	s_cselect_b32 s59, s11, s72
	s_cselect_b32 s58, s68, s69
	s_add_i32 m0, s21, 0xc000
	ds_read_b128 v[170:173], v155
	ds_read_b128 v[174:177], v155 offset:1024
	ds_read_b128 v[178:181], v155 offset:2048
	ds_read_b128 v[182:185], v155 offset:3072
	ds_read_b128 v[186:189], v155 offset:4096
	ds_read_b128 v[214:217], v155 offset:5120
	ds_read_b128 v[218:221], v155 offset:6144
	ds_read_b128 v[222:225], v155 offset:7168
	global_load_lds_dwordx4 v146, s[22:23]
	s_add_i32 m0, s21, 0xe000
	s_nop 0
	global_load_lds_dwordx4 v148, s[22:23]
	s_waitcnt lgkmcnt(8)
	s_barrier
	s_waitcnt lgkmcnt(0)
	s_setprio 1
	s_waitcnt lgkmcnt(0)
	v_mfma_f32_16x16x32_bf16 v[124:127], v[128:131], v[170:173], v[124:127]
	v_mfma_f32_16x16x32_bf16 v[120:123], v[136:139], v[170:173], v[120:123]
	v_mfma_f32_16x16x32_bf16 v[108:111], v[128:131], v[178:181], v[108:111]
	v_mfma_f32_16x16x32_bf16 v[104:107], v[136:139], v[178:181], v[104:107]
	v_mfma_f32_16x16x32_bf16 v[92:95], v[128:131], v[186:189], v[92:95]
	v_mfma_f32_16x16x32_bf16 v[88:91], v[136:139], v[186:189], v[88:91]
	v_mfma_f32_16x16x32_bf16 v[76:79], v[128:131], v[218:221], v[76:79]
	v_mfma_f32_16x16x32_bf16 v[72:75], v[136:139], v[218:221], v[72:75]
	v_mfma_f32_16x16x32_bf16 v[124:127], v[132:135], v[174:177], v[124:127]
	v_mfma_f32_16x16x32_bf16 v[120:123], v[166:169], v[174:177], v[120:123]
	v_mfma_f32_16x16x32_bf16 v[108:111], v[132:135], v[182:185], v[108:111]
	v_mfma_f32_16x16x32_bf16 v[104:107], v[166:169], v[182:185], v[104:107]
	v_mfma_f32_16x16x32_bf16 v[92:95], v[132:135], v[214:217], v[92:95]
	v_mfma_f32_16x16x32_bf16 v[88:91], v[166:169], v[214:217], v[88:91]
	v_mfma_f32_16x16x32_bf16 v[76:79], v[132:135], v[222:225], v[76:79]
	v_mfma_f32_16x16x32_bf16 v[72:75], v[166:169], v[222:225], v[72:75]
	s_setprio 0
	s_barrier
	s_add_i32 s2, 0, 0x14000
	v_add_u32_e32 v150, s2, v153
	s_add_i32 s15, s74, s39
	ds_read_b128 v[226:229], v150
	ds_read_b128 v[230:233], v150 offset:1024
	ds_read_b128 v[234:237], v150 offset:2048
	ds_read_b128 v[238:241], v150 offset:3072
	v_lshl_add_u64 v[150:151], s[58:59], 0, v[158:159]
	s_mov_b32 m0, s15
	v_lshl_add_u64 v[190:191], s[58:59], 0, v[144:145]
	global_load_lds_dwordx4 v158, s[58:59]
	s_add_i32 m0, s15, 0x2000
	s_nop 0
	global_load_lds_dwordx4 v144, s[58:59]
	s_barrier
	s_waitcnt lgkmcnt(0)
	s_setprio 1
	s_waitcnt lgkmcnt(0)
	v_mfma_f32_16x16x32_bf16 v[116:119], v[226:229], v[170:173], v[116:119]
	v_mfma_f32_16x16x32_bf16 v[112:115], v[234:237], v[170:173], v[112:115]
	v_mfma_f32_16x16x32_bf16 v[100:103], v[226:229], v[178:181], v[100:103]
	v_mfma_f32_16x16x32_bf16 v[96:99], v[234:237], v[178:181], v[96:99]
	v_mfma_f32_16x16x32_bf16 v[84:87], v[226:229], v[186:189], v[84:87]
	v_mfma_f32_16x16x32_bf16 v[80:83], v[234:237], v[186:189], v[80:83]
	v_mfma_f32_16x16x32_bf16 v[68:71], v[226:229], v[218:221], v[68:71]
	v_mfma_f32_16x16x32_bf16 v[64:67], v[234:237], v[218:221], v[64:67]
	v_mfma_f32_16x16x32_bf16 v[116:119], v[230:233], v[174:177], v[116:119]
	v_mfma_f32_16x16x32_bf16 v[112:115], v[238:241], v[174:177], v[112:115]
	v_mfma_f32_16x16x32_bf16 v[100:103], v[230:233], v[182:185], v[100:103]
	v_mfma_f32_16x16x32_bf16 v[96:99], v[238:241], v[182:185], v[96:99]
	v_mfma_f32_16x16x32_bf16 v[84:87], v[230:233], v[214:217], v[84:87]
	v_mfma_f32_16x16x32_bf16 v[80:83], v[238:241], v[214:217], v[80:83]
	v_mfma_f32_16x16x32_bf16 v[68:71], v[230:233], v[222:225], v[68:71]
	v_mfma_f32_16x16x32_bf16 v[64:67], v[238:241], v[222:225], v[64:67]
	s_setprio 0
	s_mov_b32 m0, s21
	v_lshl_add_u64 v[202:203], s[62:63], 0, v[140:141]
	s_barrier
	ds_read_b128 v[170:173], v155 offset:16384
	ds_read_b128 v[174:177], v155 offset:17408
	ds_read_b128 v[178:181], v155 offset:18432
	ds_read_b128 v[182:185], v155 offset:19456
	ds_read_b128 v[186:189], v155 offset:20480
	ds_read_b128 v[214:217], v155 offset:21504
	ds_read_b128 v[218:221], v155 offset:22528
	ds_read_b128 v[222:225], v155 offset:23552
	global_load_lds_dwordx4 v140, s[62:63]
	v_lshl_add_u64 v[204:205], s[62:63], 0, v[142:143]
	s_mov_b32 m0, s43
	s_nop 0
	global_load_lds_dwordx4 v142, s[62:63]
	s_barrier
	s_waitcnt lgkmcnt(0)
	s_setprio 1
	s_waitcnt lgkmcnt(0)
	v_mfma_f32_16x16x32_bf16 v[60:63], v[128:131], v[170:173], v[60:63]
	v_mfma_f32_16x16x32_bf16 v[56:59], v[136:139], v[170:173], v[56:59]
	v_mfma_f32_16x16x32_bf16 v[44:47], v[128:131], v[178:181], v[44:47]
	v_mfma_f32_16x16x32_bf16 v[40:43], v[136:139], v[178:181], v[40:43]
	v_mfma_f32_16x16x32_bf16 v[28:31], v[128:131], v[186:189], v[28:31]
	v_mfma_f32_16x16x32_bf16 v[24:27], v[136:139], v[186:189], v[24:27]
	v_mfma_f32_16x16x32_bf16 v[12:15], v[128:131], v[218:221], v[12:15]
	v_mfma_f32_16x16x32_bf16 v[8:11], v[136:139], v[218:221], v[8:11]
	v_mfma_f32_16x16x32_bf16 v[60:63], v[132:135], v[174:177], v[60:63]
	v_mfma_f32_16x16x32_bf16 v[56:59], v[166:169], v[174:177], v[56:59]
	v_mfma_f32_16x16x32_bf16 v[44:47], v[132:135], v[182:185], v[44:47]
	v_mfma_f32_16x16x32_bf16 v[40:43], v[166:169], v[182:185], v[40:43]
	v_mfma_f32_16x16x32_bf16 v[28:31], v[132:135], v[214:217], v[28:31]
	v_mfma_f32_16x16x32_bf16 v[24:27], v[166:169], v[214:217], v[24:27]
	v_mfma_f32_16x16x32_bf16 v[12:15], v[132:135], v[222:225], v[12:15]
	v_mfma_f32_16x16x32_bf16 v[8:11], v[166:169], v[222:225], v[8:11]
	s_setprio 0
	s_barrier
	s_add_u32 s74, s58, 0x40000
	s_addc_u32 s75, s59, 0
	s_add_i32 s2, s2, s39
	s_mov_b32 m0, s2
	s_nop 0
	global_load_lds_dwordx4 v158, s[74:75]
	s_add_i32 m0, s2, 0x2000
	s_nop 0
	global_load_lds_dwordx4 v144, s[74:75]
	s_waitcnt vmcnt(6)
	s_barrier
	s_setprio 1
	v_mfma_f32_16x16x32_bf16 v[52:55], v[226:229], v[170:173], v[52:55]
	v_mfma_f32_16x16x32_bf16 v[48:51], v[234:237], v[170:173], v[48:51]
	v_mfma_f32_16x16x32_bf16 v[36:39], v[226:229], v[178:181], v[36:39]
	v_mfma_f32_16x16x32_bf16 v[32:35], v[234:237], v[178:181], v[32:35]
	v_mfma_f32_16x16x32_bf16 v[20:23], v[226:229], v[186:189], v[20:23]
	v_mfma_f32_16x16x32_bf16 v[16:19], v[234:237], v[186:189], v[16:19]
	v_mfma_f32_16x16x32_bf16 v[4:7], v[226:229], v[218:221], v[4:7]
	v_mfma_f32_16x16x32_bf16 v[0:3], v[234:237], v[218:221], v[0:3]
	v_mfma_f32_16x16x32_bf16 v[52:55], v[230:233], v[174:177], v[52:55]
	v_mfma_f32_16x16x32_bf16 v[48:51], v[238:241], v[174:177], v[48:51]
	v_mfma_f32_16x16x32_bf16 v[36:39], v[230:233], v[182:185], v[36:39]
	v_mfma_f32_16x16x32_bf16 v[32:35], v[238:241], v[182:185], v[32:35]
	v_mfma_f32_16x16x32_bf16 v[20:23], v[230:233], v[214:217], v[20:23]
	v_mfma_f32_16x16x32_bf16 v[16:19], v[238:241], v[214:217], v[16:19]
	v_mfma_f32_16x16x32_bf16 v[4:7], v[230:233], v[222:225], v[4:7]
	v_mfma_f32_16x16x32_bf16 v[0:3], v[238:241], v[222:225], v[0:3]
	s_setprio 0
	s_add_i32 s2, 0, 0x18000
	v_add_u32_e32 v165, s2, v153
	s_barrier
	ds_read_b128 v[128:131], v165
	ds_read_b128 v[132:135], v165 offset:1024
	ds_read_b128 v[136:139], v165 offset:2048
	ds_read_b128 v[166:169], v165 offset:3072
	s_add_u32 s62, s62, 0x40000
	s_addc_u32 s63, s63, 0
	s_mov_b32 m0, s47
	ds_read_b128 v[170:173], v155 offset:32768
	ds_read_b128 v[174:177], v155 offset:33792
	ds_read_b128 v[178:181], v155 offset:34816
	ds_read_b128 v[182:185], v155 offset:35840
	ds_read_b128 v[186:189], v155 offset:36864
	ds_read_b128 v[214:217], v155 offset:37888
	ds_read_b128 v[218:221], v155 offset:38912
	ds_read_b128 v[222:225], v155 offset:39936
	global_load_lds_dwordx4 v140, s[62:63]
	s_mov_b32 m0, s48
	s_nop 0
	global_load_lds_dwordx4 v142, s[62:63]
	s_waitcnt lgkmcnt(8)
	s_barrier
	s_waitcnt lgkmcnt(0)
	s_setprio 1
	s_waitcnt lgkmcnt(0)
	v_mfma_f32_16x16x32_bf16 v[124:127], v[128:131], v[170:173], v[124:127]
	v_mfma_f32_16x16x32_bf16 v[120:123], v[136:139], v[170:173], v[120:123]
	v_mfma_f32_16x16x32_bf16 v[108:111], v[128:131], v[178:181], v[108:111]
	v_mfma_f32_16x16x32_bf16 v[104:107], v[136:139], v[178:181], v[104:107]
	v_mfma_f32_16x16x32_bf16 v[92:95], v[128:131], v[186:189], v[92:95]
	v_mfma_f32_16x16x32_bf16 v[88:91], v[136:139], v[186:189], v[88:91]
	v_mfma_f32_16x16x32_bf16 v[76:79], v[128:131], v[218:221], v[76:79]
	v_mfma_f32_16x16x32_bf16 v[72:75], v[136:139], v[218:221], v[72:75]
	v_mfma_f32_16x16x32_bf16 v[124:127], v[132:135], v[174:177], v[124:127]
	v_mfma_f32_16x16x32_bf16 v[120:123], v[166:169], v[174:177], v[120:123]
	v_mfma_f32_16x16x32_bf16 v[108:111], v[132:135], v[182:185], v[108:111]
	v_mfma_f32_16x16x32_bf16 v[104:107], v[166:169], v[182:185], v[104:107]
	v_mfma_f32_16x16x32_bf16 v[92:95], v[132:135], v[214:217], v[92:95]
	v_mfma_f32_16x16x32_bf16 v[88:91], v[166:169], v[214:217], v[88:91]
	v_mfma_f32_16x16x32_bf16 v[76:79], v[132:135], v[222:225], v[76:79]
	v_mfma_f32_16x16x32_bf16 v[72:75], v[166:169], v[222:225], v[72:75]
	s_setprio 0
	s_barrier
	s_add_i32 s15, 0, 0x1c000
	s_add_i32 s2, s2, s39
	v_add_u32_e32 v165, s15, v153
	v_lshl_add_u64 v[150:151], v[150:151], 0, s[70:71]
	s_mov_b32 m0, s2
	ds_read_b128 v[226:229], v165
	ds_read_b128 v[230:233], v165 offset:1024
	ds_read_b128 v[234:237], v165 offset:2048
	ds_read_b128 v[238:241], v165 offset:3072
	global_load_lds_dwordx4 v[150:151], off
	v_lshl_add_u64 v[150:151], v[190:191], 0, s[70:71]
	s_add_i32 m0, s2, 0x2000
	s_nop 0
	global_load_lds_dwordx4 v[150:151], off
	s_barrier
	s_waitcnt lgkmcnt(0)
	s_setprio 1
	s_waitcnt lgkmcnt(0)
	v_mfma_f32_16x16x32_bf16 v[116:119], v[226:229], v[170:173], v[116:119]
	v_mfma_f32_16x16x32_bf16 v[112:115], v[234:237], v[170:173], v[112:115]
	v_mfma_f32_16x16x32_bf16 v[100:103], v[226:229], v[178:181], v[100:103]
	v_mfma_f32_16x16x32_bf16 v[96:99], v[234:237], v[178:181], v[96:99]
	v_mfma_f32_16x16x32_bf16 v[84:87], v[226:229], v[186:189], v[84:87]
	v_mfma_f32_16x16x32_bf16 v[80:83], v[234:237], v[186:189], v[80:83]
	v_mfma_f32_16x16x32_bf16 v[68:71], v[226:229], v[218:221], v[68:71]
	v_mfma_f32_16x16x32_bf16 v[64:67], v[234:237], v[218:221], v[64:67]
	v_mfma_f32_16x16x32_bf16 v[116:119], v[230:233], v[174:177], v[116:119]
	v_mfma_f32_16x16x32_bf16 v[112:115], v[238:241], v[174:177], v[112:115]
	v_mfma_f32_16x16x32_bf16 v[100:103], v[230:233], v[182:185], v[100:103]
	v_mfma_f32_16x16x32_bf16 v[96:99], v[238:241], v[182:185], v[96:99]
	v_mfma_f32_16x16x32_bf16 v[84:87], v[230:233], v[214:217], v[84:87]
	v_mfma_f32_16x16x32_bf16 v[80:83], v[238:241], v[214:217], v[80:83]
	v_mfma_f32_16x16x32_bf16 v[68:71], v[230:233], v[222:225], v[68:71]
	v_mfma_f32_16x16x32_bf16 v[64:67], v[238:241], v[222:225], v[64:67]
	s_setprio 0
	s_mov_b32 m0, s50
	v_lshl_add_u64 v[150:151], v[202:203], 0, s[70:71]
	s_barrier
	ds_read_b128 v[170:173], v155 offset:49152
	ds_read_b128 v[174:177], v155 offset:50176
	ds_read_b128 v[178:181], v155 offset:51200
	ds_read_b128 v[182:185], v155 offset:52224
	ds_read_b128 v[186:189], v155 offset:53248
	ds_read_b128 v[214:217], v155 offset:54272
	ds_read_b128 v[218:221], v155 offset:55296
	ds_read_b128 v[222:225], v155 offset:56320
	global_load_lds_dwordx4 v[150:151], off
	v_lshl_add_u64 v[150:151], v[204:205], 0, s[70:71]
	s_mov_b32 m0, s51
	s_nop 0
	global_load_lds_dwordx4 v[150:151], off
	s_barrier
	s_waitcnt lgkmcnt(0)
	s_setprio 1
	s_waitcnt lgkmcnt(0)
	v_mfma_f32_16x16x32_bf16 v[60:63], v[128:131], v[170:173], v[60:63]
	v_mfma_f32_16x16x32_bf16 v[56:59], v[136:139], v[170:173], v[56:59]
	v_mfma_f32_16x16x32_bf16 v[44:47], v[128:131], v[178:181], v[44:47]
	v_mfma_f32_16x16x32_bf16 v[40:43], v[136:139], v[178:181], v[40:43]
	v_mfma_f32_16x16x32_bf16 v[28:31], v[128:131], v[186:189], v[28:31]
	v_mfma_f32_16x16x32_bf16 v[24:27], v[136:139], v[186:189], v[24:27]
	v_mfma_f32_16x16x32_bf16 v[12:15], v[128:131], v[218:221], v[12:15]
	v_mfma_f32_16x16x32_bf16 v[8:11], v[136:139], v[218:221], v[8:11]
	v_mfma_f32_16x16x32_bf16 v[60:63], v[132:135], v[174:177], v[60:63]
	v_mfma_f32_16x16x32_bf16 v[56:59], v[166:169], v[174:177], v[56:59]
	v_mfma_f32_16x16x32_bf16 v[44:47], v[132:135], v[182:185], v[44:47]
	v_mfma_f32_16x16x32_bf16 v[40:43], v[166:169], v[182:185], v[40:43]
	v_mfma_f32_16x16x32_bf16 v[28:31], v[132:135], v[214:217], v[28:31]
	v_mfma_f32_16x16x32_bf16 v[24:27], v[166:169], v[214:217], v[24:27]
	v_mfma_f32_16x16x32_bf16 v[12:15], v[132:135], v[222:225], v[12:15]
	v_mfma_f32_16x16x32_bf16 v[8:11], v[166:169], v[222:225], v[8:11]
	s_setprio 0
	s_barrier
	s_add_u32 s58, s58, 0x40080
	s_addc_u32 s59, s59, 0
	s_add_i32 s2, s15, s39
	s_mov_b32 m0, s2
	s_nop 0
	global_load_lds_dwordx4 v158, s[58:59]
	s_add_i32 m0, s2, 0x2000
	s_nop 0
	global_load_lds_dwordx4 v144, s[58:59]
	s_waitcnt vmcnt(6)
	s_barrier
	s_setprio 1
	v_mfma_f32_16x16x32_bf16 v[52:55], v[226:229], v[170:173], v[52:55]
	v_mfma_f32_16x16x32_bf16 v[48:51], v[234:237], v[170:173], v[48:51]
	v_mfma_f32_16x16x32_bf16 v[36:39], v[226:229], v[178:181], v[36:39]
	v_mfma_f32_16x16x32_bf16 v[32:35], v[234:237], v[178:181], v[32:35]
	v_mfma_f32_16x16x32_bf16 v[20:23], v[226:229], v[186:189], v[20:23]
	v_mfma_f32_16x16x32_bf16 v[16:19], v[234:237], v[186:189], v[16:19]
	v_mfma_f32_16x16x32_bf16 v[4:7], v[226:229], v[218:221], v[4:7]
	v_mfma_f32_16x16x32_bf16 v[0:3], v[234:237], v[218:221], v[0:3]
	v_mfma_f32_16x16x32_bf16 v[52:55], v[230:233], v[174:177], v[52:55]
	v_mfma_f32_16x16x32_bf16 v[48:51], v[238:241], v[174:177], v[48:51]
	v_mfma_f32_16x16x32_bf16 v[36:39], v[230:233], v[182:185], v[36:39]
	v_mfma_f32_16x16x32_bf16 v[32:35], v[238:241], v[182:185], v[32:35]
	v_mfma_f32_16x16x32_bf16 v[20:23], v[230:233], v[214:217], v[20:23]
	v_mfma_f32_16x16x32_bf16 v[16:19], v[238:241], v[214:217], v[16:19]
	v_mfma_f32_16x16x32_bf16 v[4:7], v[230:233], v[222:225], v[4:7]
	v_mfma_f32_16x16x32_bf16 v[0:3], v[238:241], v[222:225], v[0:3]
	s_setprio 0
	s_add_i32 s73, s73, 2
	s_add_u32 s22, s22, 0x100
	s_addc_u32 s23, s23, 0
	s_add_u32 s69, s69, 0x100
	s_addc_u32 s72, s72, 0
	s_cmp_gt_u32 s73, 13
	s_barrier
	s_cbranch_scc0 .LBB0_49

.LBB0_161:
	s_ashr_i32 s13, s12, 31
	v_cmp_lt_i64_e32 vcc, s[16:17], v[162:163]
	s_lshl_b64 s[16:17], s[12:13], 19
	s_add_u32 s16, s96, s16
	s_addc_u32 s17, s97, s17
	s_and_b64 s[18:19], vcc, exec
	s_cselect_b32 s9, s17, s23
	s_cselect_b32 s13, s16, s22
	s_ashr_i32 s11, s10, 31
	s_lshl_b64 s[18:19], s[10:11], 19
	s_add_u32 s18, s35, s18
	s_addc_u32 s19, s39, s19
	s_and_b64 s[62:63], vcc, exec
	s_cselect_b32 s11, s19, s59
	s_cselect_b32 s21, s18, s58
	s_add_u32 s22, s22, 0x40080
	s_addc_u32 s23, s23, 0
	s_add_u32 s68, s58, 0x100
	s_addc_u32 s69, s59, 0
	s_mov_b32 s72, -2
	s_add_u32 s2, s22, 0xfffc0080
	s_addc_u32 s15, s23, -1
	s_add_i32 s73, 0, 0x10000
	v_add_u32_e32 v138, s73, v142
	ds_read_b128 v[146:149], v138
	ds_read_b128 v[150:153], v138 offset:1024
	ds_read_b128 v[166:169], v138 offset:2048
	ds_read_b128 v[170:173], v138 offset:3072
	s_cmp_eq_u32 s72, 12
	s_cselect_b32 s63, s9, s15
	s_cselect_b32 s62, s13, s2
	s_cselect_b32 s59, s11, s69
	s_cselect_b32 s58, s21, s68
	s_add_i32 m0, s43, 0xc000
	ds_read_b128 v[174:177], v145
	ds_read_b128 v[178:181], v145 offset:1024
	ds_read_b128 v[182:185], v145 offset:2048
	ds_read_b128 v[186:189], v145 offset:3072
	ds_read_b128 v[214:217], v145 offset:4096
	ds_read_b128 v[218:221], v145 offset:5120
	ds_read_b128 v[222:225], v145 offset:6144
	ds_read_b128 v[226:229], v145 offset:7168
	global_load_lds_dwordx4 v134, s[22:23]
	s_add_i32 m0, s43, 0xe000
	s_nop 0
	global_load_lds_dwordx4 v136, s[22:23]
	s_waitcnt lgkmcnt(8)
	s_barrier
	s_waitcnt lgkmcnt(0)
	s_setprio 1
	s_waitcnt lgkmcnt(0)
	v_mfma_f32_16x16x32_bf16 v[124:127], v[146:149], v[174:177], 0
	v_mfma_f32_16x16x32_bf16 v[120:123], v[166:169], v[174:177], 0
	v_mfma_f32_16x16x32_bf16 v[108:111], v[146:149], v[182:185], 0
	v_mfma_f32_16x16x32_bf16 v[104:107], v[166:169], v[182:185], 0
	v_mfma_f32_16x16x32_bf16 v[92:95], v[146:149], v[214:217], 0
	v_mfma_f32_16x16x32_bf16 v[88:91], v[166:169], v[214:217], 0
	v_mfma_f32_16x16x32_bf16 v[76:79], v[146:149], v[222:225], 0
	v_mfma_f32_16x16x32_bf16 v[72:75], v[166:169], v[222:225], 0
	v_mfma_f32_16x16x32_bf16 v[124:127], v[150:153], v[178:181], v[124:127]
	v_mfma_f32_16x16x32_bf16 v[120:123], v[170:173], v[178:181], v[120:123]
	v_mfma_f32_16x16x32_bf16 v[108:111], v[150:153], v[186:189], v[108:111]
	v_mfma_f32_16x16x32_bf16 v[104:107], v[170:173], v[186:189], v[104:107]
	v_mfma_f32_16x16x32_bf16 v[92:95], v[150:153], v[218:221], v[92:95]
	v_mfma_f32_16x16x32_bf16 v[88:91], v[170:173], v[218:221], v[88:91]
	v_mfma_f32_16x16x32_bf16 v[76:79], v[150:153], v[226:229], v[76:79]
	v_mfma_f32_16x16x32_bf16 v[72:75], v[170:173], v[226:229], v[72:75]
	s_setprio 0
	s_barrier
	s_add_i32 s2, 0, 0x14000
	v_add_u32_e32 v138, s2, v142
	s_add_i32 s15, s73, s31
	ds_read_b128 v[230:233], v138
	ds_read_b128 v[234:237], v138 offset:1024
	ds_read_b128 v[238:241], v138 offset:2048
	ds_read_b128 v[242:245], v138 offset:3072
	v_lshl_add_u64 v[138:139], s[58:59], 0, v[158:159]
	s_mov_b32 m0, s15
	v_lshl_add_u64 v[154:155], s[58:59], 0, v[132:133]
	global_load_lds_dwordx4 v158, s[58:59]
	s_add_i32 m0, s15, 0x2000
	s_nop 0
	global_load_lds_dwordx4 v132, s[58:59]
	s_barrier
	s_waitcnt lgkmcnt(0)
	s_setprio 1
	s_waitcnt lgkmcnt(0)
	v_mfma_f32_16x16x32_bf16 v[116:119], v[230:233], v[174:177], 0
	v_mfma_f32_16x16x32_bf16 v[112:115], v[238:241], v[174:177], 0
	v_mfma_f32_16x16x32_bf16 v[100:103], v[230:233], v[182:185], 0
	v_mfma_f32_16x16x32_bf16 v[96:99], v[238:241], v[182:185], 0
	v_mfma_f32_16x16x32_bf16 v[84:87], v[230:233], v[214:217], 0
	v_mfma_f32_16x16x32_bf16 v[80:83], v[238:241], v[214:217], 0
	v_mfma_f32_16x16x32_bf16 v[68:71], v[230:233], v[222:225], 0
	v_mfma_f32_16x16x32_bf16 v[64:67], v[238:241], v[222:225], 0
	v_mfma_f32_16x16x32_bf16 v[116:119], v[234:237], v[178:181], v[116:119]
	v_mfma_f32_16x16x32_bf16 v[112:115], v[242:245], v[178:181], v[112:115]
	v_mfma_f32_16x16x32_bf16 v[100:103], v[234:237], v[186:189], v[100:103]
	v_mfma_f32_16x16x32_bf16 v[96:99], v[242:245], v[186:189], v[96:99]
	v_mfma_f32_16x16x32_bf16 v[84:87], v[234:237], v[218:221], v[84:87]
	v_mfma_f32_16x16x32_bf16 v[80:83], v[242:245], v[218:221], v[80:83]
	v_mfma_f32_16x16x32_bf16 v[68:71], v[234:237], v[226:229], v[68:71]
	v_mfma_f32_16x16x32_bf16 v[64:67], v[242:245], v[226:229], v[64:67]
	s_setprio 0
	s_mov_b32 m0, s43
	v_lshl_add_u64 v[190:191], s[62:63], 0, v[128:129]
	s_barrier
	ds_read_b128 v[174:177], v145 offset:16384
	ds_read_b128 v[178:181], v145 offset:17408
	ds_read_b128 v[182:185], v145 offset:18432
	ds_read_b128 v[186:189], v145 offset:19456
	ds_read_b128 v[214:217], v145 offset:20480
	ds_read_b128 v[218:221], v145 offset:21504
	ds_read_b128 v[222:225], v145 offset:22528
	ds_read_b128 v[226:229], v145 offset:23552
	global_load_lds_dwordx4 v128, s[62:63]
	v_lshl_add_u64 v[202:203], s[62:63], 0, v[130:131]
	s_mov_b32 m0, s47
	s_nop 0
	global_load_lds_dwordx4 v130, s[62:63]
	s_barrier
	s_waitcnt lgkmcnt(0)
	s_setprio 1
	s_waitcnt lgkmcnt(0)
	v_mfma_f32_16x16x32_bf16 v[60:63], v[146:149], v[174:177], 0
	v_mfma_f32_16x16x32_bf16 v[56:59], v[166:169], v[174:177], 0
	v_mfma_f32_16x16x32_bf16 v[44:47], v[146:149], v[182:185], 0
	v_mfma_f32_16x16x32_bf16 v[40:43], v[166:169], v[182:185], 0
	v_mfma_f32_16x16x32_bf16 v[28:31], v[146:149], v[214:217], 0
	v_mfma_f32_16x16x32_bf16 v[24:27], v[166:169], v[214:217], 0
	v_mfma_f32_16x16x32_bf16 v[12:15], v[146:149], v[222:225], 0
	v_mfma_f32_16x16x32_bf16 v[8:11], v[166:169], v[222:225], 0
	v_mfma_f32_16x16x32_bf16 v[60:63], v[150:153], v[178:181], v[60:63]
	v_mfma_f32_16x16x32_bf16 v[56:59], v[170:173], v[178:181], v[56:59]
	v_mfma_f32_16x16x32_bf16 v[44:47], v[150:153], v[186:189], v[44:47]
	v_mfma_f32_16x16x32_bf16 v[40:43], v[170:173], v[186:189], v[40:43]
	v_mfma_f32_16x16x32_bf16 v[28:31], v[150:153], v[218:221], v[28:31]
	v_mfma_f32_16x16x32_bf16 v[24:27], v[170:173], v[218:221], v[24:27]
	v_mfma_f32_16x16x32_bf16 v[12:15], v[150:153], v[226:229], v[12:15]
	v_mfma_f32_16x16x32_bf16 v[8:11], v[170:173], v[226:229], v[8:11]
	s_setprio 0
	s_barrier
	s_add_u32 s74, s58, 0x40000
	s_addc_u32 s75, s59, 0
	s_add_i32 s2, s2, s31
	s_mov_b32 m0, s2
	s_nop 0
	global_load_lds_dwordx4 v158, s[74:75]
	s_add_i32 m0, s2, 0x2000
	s_nop 0
	global_load_lds_dwordx4 v132, s[74:75]
	s_waitcnt vmcnt(6)
	s_barrier
	s_setprio 1
	v_mfma_f32_16x16x32_bf16 v[52:55], v[230:233], v[174:177], 0
	v_mfma_f32_16x16x32_bf16 v[48:51], v[238:241], v[174:177], 0
	v_mfma_f32_16x16x32_bf16 v[36:39], v[230:233], v[182:185], 0
	v_mfma_f32_16x16x32_bf16 v[32:35], v[238:241], v[182:185], 0
	v_mfma_f32_16x16x32_bf16 v[20:23], v[230:233], v[214:217], 0
	v_mfma_f32_16x16x32_bf16 v[16:19], v[238:241], v[214:217], 0
	v_mfma_f32_16x16x32_bf16 v[4:7], v[230:233], v[222:225], 0
	v_mfma_f32_16x16x32_bf16 v[0:3], v[238:241], v[222:225], 0
	v_mfma_f32_16x16x32_bf16 v[52:55], v[234:237], v[178:181], v[52:55]
	v_mfma_f32_16x16x32_bf16 v[48:51], v[242:245], v[178:181], v[48:51]
	v_mfma_f32_16x16x32_bf16 v[36:39], v[234:237], v[186:189], v[36:39]
	v_mfma_f32_16x16x32_bf16 v[32:35], v[242:245], v[186:189], v[32:35]
	v_mfma_f32_16x16x32_bf16 v[20:23], v[234:237], v[218:221], v[20:23]
	v_mfma_f32_16x16x32_bf16 v[16:19], v[242:245], v[218:221], v[16:19]
	v_mfma_f32_16x16x32_bf16 v[4:7], v[234:237], v[226:229], v[4:7]
	v_mfma_f32_16x16x32_bf16 v[0:3], v[242:245], v[226:229], v[0:3]
	s_setprio 0
	s_add_i32 s2, 0, 0x18000
	v_add_u32_e32 v140, s2, v142
	s_barrier
	ds_read_b128 v[146:149], v140
	ds_read_b128 v[150:153], v140 offset:1024
	ds_read_b128 v[166:169], v140 offset:2048
	ds_read_b128 v[170:173], v140 offset:3072
	s_add_u32 s62, s62, 0x40000
	s_addc_u32 s63, s63, 0
	s_mov_b32 m0, s48
	ds_read_b128 v[174:177], v145 offset:32768
	ds_read_b128 v[178:181], v145 offset:33792
	ds_read_b128 v[182:185], v145 offset:34816
	ds_read_b128 v[186:189], v145 offset:35840
	ds_read_b128 v[214:217], v145 offset:36864
	ds_read_b128 v[218:221], v145 offset:37888
	ds_read_b128 v[222:225], v145 offset:38912
	ds_read_b128 v[226:229], v145 offset:39936
	global_load_lds_dwordx4 v128, s[62:63]
	s_mov_b32 m0, s50
	s_nop 0
	global_load_lds_dwordx4 v130, s[62:63]
	s_waitcnt lgkmcnt(8)
	s_barrier
	s_waitcnt lgkmcnt(0)
	s_setprio 1
	s_waitcnt lgkmcnt(0)
	v_mfma_f32_16x16x32_bf16 v[124:127], v[146:149], v[174:177], v[124:127]
	v_mfma_f32_16x16x32_bf16 v[120:123], v[166:169], v[174:177], v[120:123]
	v_mfma_f32_16x16x32_bf16 v[108:111], v[146:149], v[182:185], v[108:111]
	v_mfma_f32_16x16x32_bf16 v[104:107], v[166:169], v[182:185], v[104:107]
	v_mfma_f32_16x16x32_bf16 v[92:95], v[146:149], v[214:217], v[92:95]
	v_mfma_f32_16x16x32_bf16 v[88:91], v[166:169], v[214:217], v[88:91]
	v_mfma_f32_16x16x32_bf16 v[76:79], v[146:149], v[222:225], v[76:79]
	v_mfma_f32_16x16x32_bf16 v[72:75], v[166:169], v[222:225], v[72:75]
	v_mfma_f32_16x16x32_bf16 v[124:127], v[150:153], v[178:181], v[124:127]
	v_mfma_f32_16x16x32_bf16 v[120:123], v[170:173], v[178:181], v[120:123]
	v_mfma_f32_16x16x32_bf16 v[108:111], v[150:153], v[186:189], v[108:111]
	v_mfma_f32_16x16x32_bf16 v[104:107], v[170:173], v[186:189], v[104:107]
	v_mfma_f32_16x16x32_bf16 v[92:95], v[150:153], v[218:221], v[92:95]
	v_mfma_f32_16x16x32_bf16 v[88:91], v[170:173], v[218:221], v[88:91]
	v_mfma_f32_16x16x32_bf16 v[76:79], v[150:153], v[226:229], v[76:79]
	v_mfma_f32_16x16x32_bf16 v[72:75], v[170:173], v[226:229], v[72:75]
	s_setprio 0
	s_barrier
	s_add_i32 s15, 0, 0x1c000
	s_add_i32 s2, s2, s31
	v_add_u32_e32 v140, s15, v142
	v_lshl_add_u64 v[138:139], v[138:139], 0, s[70:71]
	s_mov_b32 m0, s2
	ds_read_b128 v[230:233], v140
	ds_read_b128 v[234:237], v140 offset:1024
	ds_read_b128 v[238:241], v140 offset:2048
	ds_read_b128 v[242:245], v140 offset:3072
	global_load_lds_dwordx4 v[138:139], off
	v_lshl_add_u64 v[138:139], v[154:155], 0, s[70:71]
	s_add_i32 m0, s2, 0x2000
	s_nop 0
	global_load_lds_dwordx4 v[138:139], off
	s_barrier
	s_waitcnt lgkmcnt(0)
	s_setprio 1
	s_waitcnt lgkmcnt(0)
	v_mfma_f32_16x16x32_bf16 v[116:119], v[230:233], v[174:177], v[116:119]
	v_mfma_f32_16x16x32_bf16 v[112:115], v[238:241], v[174:177], v[112:115]
	v_mfma_f32_16x16x32_bf16 v[100:103], v[230:233], v[182:185], v[100:103]
	v_mfma_f32_16x16x32_bf16 v[96:99], v[238:241], v[182:185], v[96:99]
	v_mfma_f32_16x16x32_bf16 v[84:87], v[230:233], v[214:217], v[84:87]
	v_mfma_f32_16x16x32_bf16 v[80:83], v[238:241], v[214:217], v[80:83]
	v_mfma_f32_16x16x32_bf16 v[68:71], v[230:233], v[222:225], v[68:71]
	v_mfma_f32_16x16x32_bf16 v[64:67], v[238:241], v[222:225], v[64:67]
	v_mfma_f32_16x16x32_bf16 v[116:119], v[234:237], v[178:181], v[116:119]
	v_mfma_f32_16x16x32_bf16 v[112:115], v[242:245], v[178:181], v[112:115]
	v_mfma_f32_16x16x32_bf16 v[100:103], v[234:237], v[186:189], v[100:103]
	v_mfma_f32_16x16x32_bf16 v[96:99], v[242:245], v[186:189], v[96:99]
	v_mfma_f32_16x16x32_bf16 v[84:87], v[234:237], v[218:221], v[84:87]
	v_mfma_f32_16x16x32_bf16 v[80:83], v[242:245], v[218:221], v[80:83]
	v_mfma_f32_16x16x32_bf16 v[68:71], v[234:237], v[226:229], v[68:71]
	v_mfma_f32_16x16x32_bf16 v[64:67], v[242:245], v[226:229], v[64:67]
	s_setprio 0
	s_mov_b32 m0, s51
	v_lshl_add_u64 v[138:139], v[190:191], 0, s[70:71]
	s_barrier
	ds_read_b128 v[174:177], v145 offset:49152
	ds_read_b128 v[178:181], v145 offset:50176
	ds_read_b128 v[182:185], v145 offset:51200
	ds_read_b128 v[186:189], v145 offset:52224
	ds_read_b128 v[214:217], v145 offset:53248
	ds_read_b128 v[218:221], v145 offset:54272
	ds_read_b128 v[222:225], v145 offset:55296
	ds_read_b128 v[226:229], v145 offset:56320
	global_load_lds_dwordx4 v[138:139], off
	v_lshl_add_u64 v[138:139], v[202:203], 0, s[70:71]
	s_mov_b32 m0, s65
	s_nop 0
	global_load_lds_dwordx4 v[138:139], off
	s_barrier
	s_waitcnt lgkmcnt(0)
	s_setprio 1
	s_waitcnt lgkmcnt(0)
	v_mfma_f32_16x16x32_bf16 v[60:63], v[146:149], v[174:177], v[60:63]
	v_mfma_f32_16x16x32_bf16 v[56:59], v[166:169], v[174:177], v[56:59]
	v_mfma_f32_16x16x32_bf16 v[44:47], v[146:149], v[182:185], v[44:47]
	v_mfma_f32_16x16x32_bf16 v[40:43], v[166:169], v[182:185], v[40:43]
	v_mfma_f32_16x16x32_bf16 v[28:31], v[146:149], v[214:217], v[28:31]
	v_mfma_f32_16x16x32_bf16 v[24:27], v[166:169], v[214:217], v[24:27]
	v_mfma_f32_16x16x32_bf16 v[12:15], v[146:149], v[222:225], v[12:15]
	v_mfma_f32_16x16x32_bf16 v[8:11], v[166:169], v[222:225], v[8:11]
	v_mfma_f32_16x16x32_bf16 v[60:63], v[150:153], v[178:181], v[60:63]
	v_mfma_f32_16x16x32_bf16 v[56:59], v[170:173], v[178:181], v[56:59]
	v_mfma_f32_16x16x32_bf16 v[44:47], v[150:153], v[186:189], v[44:47]
	v_mfma_f32_16x16x32_bf16 v[40:43], v[170:173], v[186:189], v[40:43]
	v_mfma_f32_16x16x32_bf16 v[28:31], v[150:153], v[218:221], v[28:31]
	v_mfma_f32_16x16x32_bf16 v[24:27], v[170:173], v[218:221], v[24:27]
	v_mfma_f32_16x16x32_bf16 v[12:15], v[150:153], v[226:229], v[12:15]
	v_mfma_f32_16x16x32_bf16 v[8:11], v[170:173], v[226:229], v[8:11]
	s_setprio 0
	s_barrier
	s_add_u32 s58, s58, 0x40080
	s_addc_u32 s59, s59, 0
	s_add_i32 s2, s15, s31
	s_mov_b32 m0, s2
	s_nop 0
	global_load_lds_dwordx4 v158, s[58:59]
	s_add_i32 m0, s2, 0x2000
	s_nop 0
	global_load_lds_dwordx4 v132, s[58:59]
	s_waitcnt vmcnt(6)
	s_barrier
	s_setprio 1
	v_mfma_f32_16x16x32_bf16 v[52:55], v[230:233], v[174:177], v[52:55]
	v_mfma_f32_16x16x32_bf16 v[48:51], v[238:241], v[174:177], v[48:51]
	v_mfma_f32_16x16x32_bf16 v[36:39], v[230:233], v[182:185], v[36:39]
	v_mfma_f32_16x16x32_bf16 v[32:35], v[238:241], v[182:185], v[32:35]
	v_mfma_f32_16x16x32_bf16 v[20:23], v[230:233], v[214:217], v[20:23]
	v_mfma_f32_16x16x32_bf16 v[16:19], v[238:241], v[214:217], v[16:19]
	v_mfma_f32_16x16x32_bf16 v[4:7], v[230:233], v[222:225], v[4:7]
	v_mfma_f32_16x16x32_bf16 v[0:3], v[238:241], v[222:225], v[0:3]
	v_mfma_f32_16x16x32_bf16 v[52:55], v[234:237], v[178:181], v[52:55]
	v_mfma_f32_16x16x32_bf16 v[48:51], v[242:245], v[178:181], v[48:51]
	v_mfma_f32_16x16x32_bf16 v[36:39], v[234:237], v[186:189], v[36:39]
	v_mfma_f32_16x16x32_bf16 v[32:35], v[242:245], v[186:189], v[32:35]
	v_mfma_f32_16x16x32_bf16 v[20:23], v[234:237], v[218:221], v[20:23]
	v_mfma_f32_16x16x32_bf16 v[16:19], v[242:245], v[218:221], v[16:19]
	v_mfma_f32_16x16x32_bf16 v[4:7], v[234:237], v[226:229], v[4:7]
	v_mfma_f32_16x16x32_bf16 v[0:3], v[242:245], v[226:229], v[0:3]
	s_setprio 0
	s_add_i32 s72, s72, 2
	s_add_u32 s22, s22, 0x100
	s_addc_u32 s23, s23, 0
	s_add_u32 s68, s68, 0x100
	s_addc_u32 s69, s69, 0
	s_cmp_gt_u32 s72, 13
	s_barrier
	s_cbranch_scc1 .Lzp_exit1
.LBB0_162:
	s_add_u32 s2, s22, 0xfffc0080
	s_addc_u32 s15, s23, -1
	s_add_i32 s73, 0, 0x10000
	v_add_u32_e32 v138, s73, v142
	ds_read_b128 v[146:149], v138
	ds_read_b128 v[150:153], v138 offset:1024
	ds_read_b128 v[166:169], v138 offset:2048
	ds_read_b128 v[170:173], v138 offset:3072
	s_cmp_eq_u32 s72, 12
	s_cselect_b32 s63, s9, s15
	s_cselect_b32 s62, s13, s2
	s_cselect_b32 s59, s11, s69
	s_cselect_b32 s58, s21, s68
	s_add_i32 m0, s43, 0xc000
	ds_read_b128 v[174:177], v145
	ds_read_b128 v[178:181], v145 offset:1024
	ds_read_b128 v[182:185], v145 offset:2048
	ds_read_b128 v[186:189], v145 offset:3072
	ds_read_b128 v[214:217], v145 offset:4096
	ds_read_b128 v[218:221], v145 offset:5120
	ds_read_b128 v[222:225], v145 offset:6144
	ds_read_b128 v[226:229], v145 offset:7168
	global_load_lds_dwordx4 v134, s[22:23]
	s_add_i32 m0, s43, 0xe000
	s_nop 0
	global_load_lds_dwordx4 v136, s[22:23]
	s_waitcnt lgkmcnt(8)
	s_barrier
	s_waitcnt lgkmcnt(0)
	s_setprio 1
	s_waitcnt lgkmcnt(0)
	v_mfma_f32_16x16x32_bf16 v[124:127], v[146:149], v[174:177], v[124:127]
	v_mfma_f32_16x16x32_bf16 v[120:123], v[166:169], v[174:177], v[120:123]
	v_mfma_f32_16x16x32_bf16 v[108:111], v[146:149], v[182:185], v[108:111]
	v_mfma_f32_16x16x32_bf16 v[104:107], v[166:169], v[182:185], v[104:107]
	v_mfma_f32_16x16x32_bf16 v[92:95], v[146:149], v[214:217], v[92:95]
	v_mfma_f32_16x16x32_bf16 v[88:91], v[166:169], v[214:217], v[88:91]
	v_mfma_f32_16x16x32_bf16 v[76:79], v[146:149], v[222:225], v[76:79]
	v_mfma_f32_16x16x32_bf16 v[72:75], v[166:169], v[222:225], v[72:75]
	v_mfma_f32_16x16x32_bf16 v[124:127], v[150:153], v[178:181], v[124:127]
	v_mfma_f32_16x16x32_bf16 v[120:123], v[170:173], v[178:181], v[120:123]
	v_mfma_f32_16x16x32_bf16 v[108:111], v[150:153], v[186:189], v[108:111]
	v_mfma_f32_16x16x32_bf16 v[104:107], v[170:173], v[186:189], v[104:107]
	v_mfma_f32_16x16x32_bf16 v[92:95], v[150:153], v[218:221], v[92:95]
	v_mfma_f32_16x16x32_bf16 v[88:91], v[170:173], v[218:221], v[88:91]
	v_mfma_f32_16x16x32_bf16 v[76:79], v[150:153], v[226:229], v[76:79]
	v_mfma_f32_16x16x32_bf16 v[72:75], v[170:173], v[226:229], v[72:75]
	s_setprio 0
	s_barrier
	s_add_i32 s2, 0, 0x14000
	v_add_u32_e32 v138, s2, v142
	s_add_i32 s15, s73, s31
	ds_read_b128 v[230:233], v138
	ds_read_b128 v[234:237], v138 offset:1024
	ds_read_b128 v[238:241], v138 offset:2048
	ds_read_b128 v[242:245], v138 offset:3072
	v_lshl_add_u64 v[138:139], s[58:59], 0, v[158:159]
	s_mov_b32 m0, s15
	v_lshl_add_u64 v[154:155], s[58:59], 0, v[132:133]
	global_load_lds_dwordx4 v158, s[58:59]
	s_add_i32 m0, s15, 0x2000
	s_nop 0
	global_load_lds_dwordx4 v132, s[58:59]
	s_barrier
	s_waitcnt lgkmcnt(0)
	s_setprio 1
	s_waitcnt lgkmcnt(0)
	v_mfma_f32_16x16x32_bf16 v[116:119], v[230:233], v[174:177], v[116:119]
	v_mfma_f32_16x16x32_bf16 v[112:115], v[238:241], v[174:177], v[112:115]
	v_mfma_f32_16x16x32_bf16 v[100:103], v[230:233], v[182:185], v[100:103]
	v_mfma_f32_16x16x32_bf16 v[96:99], v[238:241], v[182:185], v[96:99]
	v_mfma_f32_16x16x32_bf16 v[84:87], v[230:233], v[214:217], v[84:87]
	v_mfma_f32_16x16x32_bf16 v[80:83], v[238:241], v[214:217], v[80:83]
	v_mfma_f32_16x16x32_bf16 v[68:71], v[230:233], v[222:225], v[68:71]
	v_mfma_f32_16x16x32_bf16 v[64:67], v[238:241], v[222:225], v[64:67]
	v_mfma_f32_16x16x32_bf16 v[116:119], v[234:237], v[178:181], v[116:119]
	v_mfma_f32_16x16x32_bf16 v[112:115], v[242:245], v[178:181], v[112:115]
	v_mfma_f32_16x16x32_bf16 v[100:103], v[234:237], v[186:189], v[100:103]
	v_mfma_f32_16x16x32_bf16 v[96:99], v[242:245], v[186:189], v[96:99]
	v_mfma_f32_16x16x32_bf16 v[84:87], v[234:237], v[218:221], v[84:87]
	v_mfma_f32_16x16x32_bf16 v[80:83], v[242:245], v[218:221], v[80:83]
	v_mfma_f32_16x16x32_bf16 v[68:71], v[234:237], v[226:229], v[68:71]
	v_mfma_f32_16x16x32_bf16 v[64:67], v[242:245], v[226:229], v[64:67]
	s_setprio 0
	s_mov_b32 m0, s43
	v_lshl_add_u64 v[190:191], s[62:63], 0, v[128:129]
	s_barrier
	ds_read_b128 v[174:177], v145 offset:16384
	ds_read_b128 v[178:181], v145 offset:17408
	ds_read_b128 v[182:185], v145 offset:18432
	ds_read_b128 v[186:189], v145 offset:19456
	ds_read_b128 v[214:217], v145 offset:20480
	ds_read_b128 v[218:221], v145 offset:21504
	ds_read_b128 v[222:225], v145 offset:22528
	ds_read_b128 v[226:229], v145 offset:23552
	global_load_lds_dwordx4 v128, s[62:63]
	v_lshl_add_u64 v[202:203], s[62:63], 0, v[130:131]
	s_mov_b32 m0, s47
	s_nop 0
	global_load_lds_dwordx4 v130, s[62:63]
	s_barrier
	s_waitcnt lgkmcnt(0)
	s_setprio 1
	s_waitcnt lgkmcnt(0)
	v_mfma_f32_16x16x32_bf16 v[60:63], v[146:149], v[174:177], v[60:63]
	v_mfma_f32_16x16x32_bf16 v[56:59], v[166:169], v[174:177], v[56:59]
	v_mfma_f32_16x16x32_bf16 v[44:47], v[146:149], v[182:185], v[44:47]
	v_mfma_f32_16x16x32_bf16 v[40:43], v[166:169], v[182:185], v[40:43]
	v_mfma_f32_16x16x32_bf16 v[28:31], v[146:149], v[214:217], v[28:31]
	v_mfma_f32_16x16x32_bf16 v[24:27], v[166:169], v[214:217], v[24:27]
	v_mfma_f32_16x16x32_bf16 v[12:15], v[146:149], v[222:225], v[12:15]
	v_mfma_f32_16x16x32_bf16 v[8:11], v[166:169], v[222:225], v[8:11]
	v_mfma_f32_16x16x32_bf16 v[60:63], v[150:153], v[178:181], v[60:63]
	v_mfma_f32_16x16x32_bf16 v[56:59], v[170:173], v[178:181], v[56:59]
	v_mfma_f32_16x16x32_bf16 v[44:47], v[150:153], v[186:189], v[44:47]
	v_mfma_f32_16x16x32_bf16 v[40:43], v[170:173], v[186:189], v[40:43]
	v_mfma_f32_16x16x32_bf16 v[28:31], v[150:153], v[218:221], v[28:31]
	v_mfma_f32_16x16x32_bf16 v[24:27], v[170:173], v[218:221], v[24:27]
	v_mfma_f32_16x16x32_bf16 v[12:15], v[150:153], v[226:229], v[12:15]
	v_mfma_f32_16x16x32_bf16 v[8:11], v[170:173], v[226:229], v[8:11]
	s_setprio 0
	s_barrier
	s_add_u32 s74, s58, 0x40000
	s_addc_u32 s75, s59, 0
	s_add_i32 s2, s2, s31
	s_mov_b32 m0, s2
	s_nop 0
	global_load_lds_dwordx4 v158, s[74:75]
	s_add_i32 m0, s2, 0x2000
	s_nop 0
	global_load_lds_dwordx4 v132, s[74:75]
	s_waitcnt vmcnt(6)
	s_barrier
	s_setprio 1
	v_mfma_f32_16x16x32_bf16 v[52:55], v[230:233], v[174:177], v[52:55]
	v_mfma_f32_16x16x32_bf16 v[48:51], v[238:241], v[174:177], v[48:51]
	v_mfma_f32_16x16x32_bf16 v[36:39], v[230:233], v[182:185], v[36:39]
	v_mfma_f32_16x16x32_bf16 v[32:35], v[238:241], v[182:185], v[32:35]
	v_mfma_f32_16x16x32_bf16 v[20:23], v[230:233], v[214:217], v[20:23]
	v_mfma_f32_16x16x32_bf16 v[16:19], v[238:241], v[214:217], v[16:19]
	v_mfma_f32_16x16x32_bf16 v[4:7], v[230:233], v[222:225], v[4:7]
	v_mfma_f32_16x16x32_bf16 v[0:3], v[238:241], v[222:225], v[0:3]
	v_mfma_f32_16x16x32_bf16 v[52:55], v[234:237], v[178:181], v[52:55]
	v_mfma_f32_16x16x32_bf16 v[48:51], v[242:245], v[178:181], v[48:51]
	v_mfma_f32_16x16x32_bf16 v[36:39], v[234:237], v[186:189], v[36:39]
	v_mfma_f32_16x16x32_bf16 v[32:35], v[242:245], v[186:189], v[32:35]
	v_mfma_f32_16x16x32_bf16 v[20:23], v[234:237], v[218:221], v[20:23]
	v_mfma_f32_16x16x32_bf16 v[16:19], v[242:245], v[218:221], v[16:19]
	v_mfma_f32_16x16x32_bf16 v[4:7], v[234:237], v[226:229], v[4:7]
	v_mfma_f32_16x16x32_bf16 v[0:3], v[242:245], v[226:229], v[0:3]
	s_setprio 0
	s_add_i32 s2, 0, 0x18000
	v_add_u32_e32 v140, s2, v142
	s_barrier
	ds_read_b128 v[146:149], v140
	ds_read_b128 v[150:153], v140 offset:1024
	ds_read_b128 v[166:169], v140 offset:2048
	ds_read_b128 v[170:173], v140 offset:3072
	s_add_u32 s62, s62, 0x40000
	s_addc_u32 s63, s63, 0
	s_mov_b32 m0, s48
	ds_read_b128 v[174:177], v145 offset:32768
	ds_read_b128 v[178:181], v145 offset:33792
	ds_read_b128 v[182:185], v145 offset:34816
	ds_read_b128 v[186:189], v145 offset:35840
	ds_read_b128 v[214:217], v145 offset:36864
	ds_read_b128 v[218:221], v145 offset:37888
	ds_read_b128 v[222:225], v145 offset:38912
	ds_read_b128 v[226:229], v145 offset:39936
	global_load_lds_dwordx4 v128, s[62:63]
	s_mov_b32 m0, s50
	s_nop 0
	global_load_lds_dwordx4 v130, s[62:63]
	s_waitcnt lgkmcnt(8)
	s_barrier
	s_waitcnt lgkmcnt(0)
	s_setprio 1
	s_waitcnt lgkmcnt(0)
	v_mfma_f32_16x16x32_bf16 v[124:127], v[146:149], v[174:177], v[124:127]
	v_mfma_f32_16x16x32_bf16 v[120:123], v[166:169], v[174:177], v[120:123]
	v_mfma_f32_16x16x32_bf16 v[108:111], v[146:149], v[182:185], v[108:111]
	v_mfma_f32_16x16x32_bf16 v[104:107], v[166:169], v[182:185], v[104:107]
	v_mfma_f32_16x16x32_bf16 v[92:95], v[146:149], v[214:217], v[92:95]
	v_mfma_f32_16x16x32_bf16 v[88:91], v[166:169], v[214:217], v[88:91]
	v_mfma_f32_16x16x32_bf16 v[76:79], v[146:149], v[222:225], v[76:79]
	v_mfma_f32_16x16x32_bf16 v[72:75], v[166:169], v[222:225], v[72:75]
	v_mfma_f32_16x16x32_bf16 v[124:127], v[150:153], v[178:181], v[124:127]
	v_mfma_f32_16x16x32_bf16 v[120:123], v[170:173], v[178:181], v[120:123]
	v_mfma_f32_16x16x32_bf16 v[108:111], v[150:153], v[186:189], v[108:111]
	v_mfma_f32_16x16x32_bf16 v[104:107], v[170:173], v[186:189], v[104:107]
	v_mfma_f32_16x16x32_bf16 v[92:95], v[150:153], v[218:221], v[92:95]
	v_mfma_f32_16x16x32_bf16 v[88:91], v[170:173], v[218:221], v[88:91]
	v_mfma_f32_16x16x32_bf16 v[76:79], v[150:153], v[226:229], v[76:79]
	v_mfma_f32_16x16x32_bf16 v[72:75], v[170:173], v[226:229], v[72:75]
	s_setprio 0
	s_barrier
	s_add_i32 s15, 0, 0x1c000
	s_add_i32 s2, s2, s31
	v_add_u32_e32 v140, s15, v142
	v_lshl_add_u64 v[138:139], v[138:139], 0, s[70:71]
	s_mov_b32 m0, s2
	ds_read_b128 v[230:233], v140
	ds_read_b128 v[234:237], v140 offset:1024
	ds_read_b128 v[238:241], v140 offset:2048
	ds_read_b128 v[242:245], v140 offset:3072
	global_load_lds_dwordx4 v[138:139], off
	v_lshl_add_u64 v[138:139], v[154:155], 0, s[70:71]
	s_add_i32 m0, s2, 0x2000
	s_nop 0
	global_load_lds_dwordx4 v[138:139], off
	s_barrier
	s_waitcnt lgkmcnt(0)
	s_setprio 1
	s_waitcnt lgkmcnt(0)
	v_mfma_f32_16x16x32_bf16 v[116:119], v[230:233], v[174:177], v[116:119]
	v_mfma_f32_16x16x32_bf16 v[112:115], v[238:241], v[174:177], v[112:115]
	v_mfma_f32_16x16x32_bf16 v[100:103], v[230:233], v[182:185], v[100:103]
	v_mfma_f32_16x16x32_bf16 v[96:99], v[238:241], v[182:185], v[96:99]
	v_mfma_f32_16x16x32_bf16 v[84:87], v[230:233], v[214:217], v[84:87]
	v_mfma_f32_16x16x32_bf16 v[80:83], v[238:241], v[214:217], v[80:83]
	v_mfma_f32_16x16x32_bf16 v[68:71], v[230:233], v[222:225], v[68:71]
	v_mfma_f32_16x16x32_bf16 v[64:67], v[238:241], v[222:225], v[64:67]
	v_mfma_f32_16x16x32_bf16 v[116:119], v[234:237], v[178:181], v[116:119]
	v_mfma_f32_16x16x32_bf16 v[112:115], v[242:245], v[178:181], v[112:115]
	v_mfma_f32_16x16x32_bf16 v[100:103], v[234:237], v[186:189], v[100:103]
	v_mfma_f32_16x16x32_bf16 v[96:99], v[242:245], v[186:189], v[96:99]
	v_mfma_f32_16x16x32_bf16 v[84:87], v[234:237], v[218:221], v[84:87]
	v_mfma_f32_16x16x32_bf16 v[80:83], v[242:245], v[218:221], v[80:83]
	v_mfma_f32_16x16x32_bf16 v[68:71], v[234:237], v[226:229], v[68:71]
	v_mfma_f32_16x16x32_bf16 v[64:67], v[242:245], v[226:229], v[64:67]
	s_setprio 0
	s_mov_b32 m0, s51
	v_lshl_add_u64 v[138:139], v[190:191], 0, s[70:71]
	s_barrier
	ds_read_b128 v[174:177], v145 offset:49152
	ds_read_b128 v[178:181], v145 offset:50176
	ds_read_b128 v[182:185], v145 offset:51200
	ds_read_b128 v[186:189], v145 offset:52224
	ds_read_b128 v[214:217], v145 offset:53248
	ds_read_b128 v[218:221], v145 offset:54272
	ds_read_b128 v[222:225], v145 offset:55296
	ds_read_b128 v[226:229], v145 offset:56320
	global_load_lds_dwordx4 v[138:139], off
	v_lshl_add_u64 v[138:139], v[202:203], 0, s[70:71]
	s_mov_b32 m0, s65
	s_nop 0
	global_load_lds_dwordx4 v[138:139], off
	s_barrier
	s_waitcnt lgkmcnt(0)
	s_setprio 1
	s_waitcnt lgkmcnt(0)
	v_mfma_f32_16x16x32_bf16 v[60:63], v[146:149], v[174:177], v[60:63]
	v_mfma_f32_16x16x32_bf16 v[56:59], v[166:169], v[174:177], v[56:59]
	v_mfma_f32_16x16x32_bf16 v[44:47], v[146:149], v[182:185], v[44:47]
	v_mfma_f32_16x16x32_bf16 v[40:43], v[166:169], v[182:185], v[40:43]
	v_mfma_f32_16x16x32_bf16 v[28:31], v[146:149], v[214:217], v[28:31]
	v_mfma_f32_16x16x32_bf16 v[24:27], v[166:169], v[214:217], v[24:27]
	v_mfma_f32_16x16x32_bf16 v[12:15], v[146:149], v[222:225], v[12:15]
	v_mfma_f32_16x16x32_bf16 v[8:11], v[166:169], v[222:225], v[8:11]
	v_mfma_f32_16x16x32_bf16 v[60:63], v[150:153], v[178:181], v[60:63]
	v_mfma_f32_16x16x32_bf16 v[56:59], v[170:173], v[178:181], v[56:59]
	v_mfma_f32_16x16x32_bf16 v[44:47], v[150:153], v[186:189], v[44:47]
	v_mfma_f32_16x16x32_bf16 v[40:43], v[170:173], v[186:189], v[40:43]
	v_mfma_f32_16x16x32_bf16 v[28:31], v[150:153], v[218:221], v[28:31]
	v_mfma_f32_16x16x32_bf16 v[24:27], v[170:173], v[218:221], v[24:27]
	v_mfma_f32_16x16x32_bf16 v[12:15], v[150:153], v[226:229], v[12:15]
	v_mfma_f32_16x16x32_bf16 v[8:11], v[170:173], v[226:229], v[8:11]
	s_setprio 0
	s_barrier
	s_add_u32 s58, s58, 0x40080
	s_addc_u32 s59, s59, 0
	s_add_i32 s2, s15, s31
	s_mov_b32 m0, s2
	s_nop 0
	global_load_lds_dwordx4 v158, s[58:59]
	s_add_i32 m0, s2, 0x2000
	s_nop 0
	global_load_lds_dwordx4 v132, s[58:59]
	s_waitcnt vmcnt(6)
	s_barrier
	s_setprio 1
	v_mfma_f32_16x16x32_bf16 v[52:55], v[230:233], v[174:177], v[52:55]
	v_mfma_f32_16x16x32_bf16 v[48:51], v[238:241], v[174:177], v[48:51]
	v_mfma_f32_16x16x32_bf16 v[36:39], v[230:233], v[182:185], v[36:39]
	v_mfma_f32_16x16x32_bf16 v[32:35], v[238:241], v[182:185], v[32:35]
	v_mfma_f32_16x16x32_bf16 v[20:23], v[230:233], v[214:217], v[20:23]
	v_mfma_f32_16x16x32_bf16 v[16:19], v[238:241], v[214:217], v[16:19]
	v_mfma_f32_16x16x32_bf16 v[4:7], v[230:233], v[222:225], v[4:7]
	v_mfma_f32_16x16x32_bf16 v[0:3], v[238:241], v[222:225], v[0:3]
	v_mfma_f32_16x16x32_bf16 v[52:55], v[234:237], v[178:181], v[52:55]
	v_mfma_f32_16x16x32_bf16 v[48:51], v[242:245], v[178:181], v[48:51]
	v_mfma_f32_16x16x32_bf16 v[36:39], v[234:237], v[186:189], v[36:39]
	v_mfma_f32_16x16x32_bf16 v[32:35], v[242:245], v[186:189], v[32:35]
	v_mfma_f32_16x16x32_bf16 v[20:23], v[234:237], v[218:221], v[20:23]
	v_mfma_f32_16x16x32_bf16 v[16:19], v[242:245], v[218:221], v[16:19]
	v_mfma_f32_16x16x32_bf16 v[4:7], v[234:237], v[226:229], v[4:7]
	v_mfma_f32_16x16x32_bf16 v[0:3], v[242:245], v[226:229], v[0:3]
	s_setprio 0
	s_add_i32 s72, s72, 2
	s_add_u32 s22, s22, 0x100
	s_addc_u32 s23, s23, 0
	s_add_u32 s68, s68, 0x100
	s_addc_u32 s69, s69, 0
	s_cmp_gt_u32 s72, 13
	s_barrier
	s_cbranch_scc0 .LBB0_162

.LBB0_533:
	v_mov_b64_e32 v[0:1], 0x300
	s_ashr_i32 s17, s16, 31
	v_cmp_lt_i64_e32 vcc, s[18:19], v[0:1]
	s_lshl_b64 s[18:19], s[16:17], 19
	s_add_u32 s18, s96, s18
	s_addc_u32 s19, s97, s19
	s_and_b64 s[20:21], vcc, exec
	s_cselect_b32 s9, s19, s25
	s_cselect_b32 s17, s18, s24
	s_ashr_i32 s11, s10, 31
	s_lshl_b64 s[20:21], s[10:11], 19
	s_add_u32 s20, s35, s20
	s_addc_u32 s21, s39, s21
	s_and_b64 s[62:63], vcc, exec
	s_cselect_b32 s11, s21, s59
	s_cselect_b32 s23, s20, s58
	s_add_u32 s24, s24, 0x40080
	s_addc_u32 s25, s25, 0
	s_add_u32 s68, s58, 0x100
	s_addc_u32 s69, s59, 0
	s_mov_b32 s72, -2
	s_add_u32 s2, s24, 0xfffc0080
	s_addc_u32 s15, s25, -1
	s_add_i32 s73, 0, 0x10000
	v_add_u32_e32 v138, s73, v142
	ds_read_b128 v[146:149], v138
	ds_read_b128 v[150:153], v138 offset:1024
	ds_read_b128 v[166:169], v138 offset:2048
	ds_read_b128 v[170:173], v138 offset:3072
	s_cmp_eq_u32 s72, 12
	s_cselect_b32 s63, s9, s15
	s_cselect_b32 s62, s17, s2
	s_cselect_b32 s59, s11, s69
	s_cselect_b32 s58, s23, s68
	s_add_i32 m0, s43, 0xc000
	ds_read_b128 v[174:177], v145
	ds_read_b128 v[178:181], v145 offset:1024
	ds_read_b128 v[182:185], v145 offset:2048
	ds_read_b128 v[186:189], v145 offset:3072
	ds_read_b128 v[214:217], v145 offset:4096
	ds_read_b128 v[218:221], v145 offset:5120
	ds_read_b128 v[222:225], v145 offset:6144
	ds_read_b128 v[226:229], v145 offset:7168
	global_load_lds_dwordx4 v134, s[24:25]
	s_add_i32 m0, s43, 0xe000
	s_nop 0
	global_load_lds_dwordx4 v136, s[24:25]
	s_waitcnt lgkmcnt(8)
	s_barrier
	s_waitcnt lgkmcnt(0)
	s_setprio 1
	s_waitcnt lgkmcnt(0)
	v_mfma_f32_16x16x32_bf16 v[124:127], v[146:149], v[174:177], 0
	v_mfma_f32_16x16x32_bf16 v[120:123], v[166:169], v[174:177], 0
	v_mfma_f32_16x16x32_bf16 v[108:111], v[146:149], v[182:185], 0
	v_mfma_f32_16x16x32_bf16 v[104:107], v[166:169], v[182:185], 0
	v_mfma_f32_16x16x32_bf16 v[92:95], v[146:149], v[214:217], 0
	v_mfma_f32_16x16x32_bf16 v[88:91], v[166:169], v[214:217], 0
	v_mfma_f32_16x16x32_bf16 v[76:79], v[146:149], v[222:225], 0
	v_mfma_f32_16x16x32_bf16 v[72:75], v[166:169], v[222:225], 0
	v_mfma_f32_16x16x32_bf16 v[124:127], v[150:153], v[178:181], v[124:127]
	v_mfma_f32_16x16x32_bf16 v[120:123], v[170:173], v[178:181], v[120:123]
	v_mfma_f32_16x16x32_bf16 v[108:111], v[150:153], v[186:189], v[108:111]
	v_mfma_f32_16x16x32_bf16 v[104:107], v[170:173], v[186:189], v[104:107]
	v_mfma_f32_16x16x32_bf16 v[92:95], v[150:153], v[218:221], v[92:95]
	v_mfma_f32_16x16x32_bf16 v[88:91], v[170:173], v[218:221], v[88:91]
	v_mfma_f32_16x16x32_bf16 v[76:79], v[150:153], v[226:229], v[76:79]
	v_mfma_f32_16x16x32_bf16 v[72:75], v[170:173], v[226:229], v[72:75]
	s_setprio 0
	s_barrier
	s_add_i32 s2, 0, 0x14000
	v_add_u32_e32 v138, s2, v142
	s_add_i32 s15, s73, s31
	ds_read_b128 v[230:233], v138
	ds_read_b128 v[234:237], v138 offset:1024
	ds_read_b128 v[238:241], v138 offset:2048
	ds_read_b128 v[242:245], v138 offset:3072
	v_lshl_add_u64 v[138:139], s[58:59], 0, v[158:159]
	s_mov_b32 m0, s15
	v_lshl_add_u64 v[154:155], s[58:59], 0, v[132:133]
	global_load_lds_dwordx4 v158, s[58:59]
	s_add_i32 m0, s15, 0x2000
	s_nop 0
	global_load_lds_dwordx4 v132, s[58:59]
	s_barrier
	s_waitcnt lgkmcnt(0)
	s_setprio 1
	s_waitcnt lgkmcnt(0)
	v_mfma_f32_16x16x32_bf16 v[116:119], v[230:233], v[174:177], 0
	v_mfma_f32_16x16x32_bf16 v[112:115], v[238:241], v[174:177], 0
	v_mfma_f32_16x16x32_bf16 v[100:103], v[230:233], v[182:185], 0
	v_mfma_f32_16x16x32_bf16 v[96:99], v[238:241], v[182:185], 0
	v_mfma_f32_16x16x32_bf16 v[84:87], v[230:233], v[214:217], 0
	v_mfma_f32_16x16x32_bf16 v[80:83], v[238:241], v[214:217], 0
	v_mfma_f32_16x16x32_bf16 v[68:71], v[230:233], v[222:225], 0
	v_mfma_f32_16x16x32_bf16 v[64:67], v[238:241], v[222:225], 0
	v_mfma_f32_16x16x32_bf16 v[116:119], v[234:237], v[178:181], v[116:119]
	v_mfma_f32_16x16x32_bf16 v[112:115], v[242:245], v[178:181], v[112:115]
	v_mfma_f32_16x16x32_bf16 v[100:103], v[234:237], v[186:189], v[100:103]
	v_mfma_f32_16x16x32_bf16 v[96:99], v[242:245], v[186:189], v[96:99]
	v_mfma_f32_16x16x32_bf16 v[84:87], v[234:237], v[218:221], v[84:87]
	v_mfma_f32_16x16x32_bf16 v[80:83], v[242:245], v[218:221], v[80:83]
	v_mfma_f32_16x16x32_bf16 v[68:71], v[234:237], v[226:229], v[68:71]
	v_mfma_f32_16x16x32_bf16 v[64:67], v[242:245], v[226:229], v[64:67]
	s_setprio 0
	s_mov_b32 m0, s43
	v_lshl_add_u64 v[190:191], s[62:63], 0, v[128:129]
	s_barrier
	ds_read_b128 v[174:177], v145 offset:16384
	ds_read_b128 v[178:181], v145 offset:17408
	ds_read_b128 v[182:185], v145 offset:18432
	ds_read_b128 v[186:189], v145 offset:19456
	ds_read_b128 v[214:217], v145 offset:20480
	ds_read_b128 v[218:221], v145 offset:21504
	ds_read_b128 v[222:225], v145 offset:22528
	ds_read_b128 v[226:229], v145 offset:23552
	global_load_lds_dwordx4 v128, s[62:63]
	v_lshl_add_u64 v[202:203], s[62:63], 0, v[130:131]
	s_mov_b32 m0, s47
	s_nop 0
	global_load_lds_dwordx4 v130, s[62:63]
	s_barrier
	s_waitcnt lgkmcnt(0)
	s_setprio 1
	s_waitcnt lgkmcnt(0)
	v_mfma_f32_16x16x32_bf16 v[60:63], v[146:149], v[174:177], 0
	v_mfma_f32_16x16x32_bf16 v[56:59], v[166:169], v[174:177], 0
	v_mfma_f32_16x16x32_bf16 v[44:47], v[146:149], v[182:185], 0
	v_mfma_f32_16x16x32_bf16 v[40:43], v[166:169], v[182:185], 0
	v_mfma_f32_16x16x32_bf16 v[28:31], v[146:149], v[214:217], 0
	v_mfma_f32_16x16x32_bf16 v[24:27], v[166:169], v[214:217], 0
	v_mfma_f32_16x16x32_bf16 v[12:15], v[146:149], v[222:225], 0
	v_mfma_f32_16x16x32_bf16 v[8:11], v[166:169], v[222:225], 0
	v_mfma_f32_16x16x32_bf16 v[60:63], v[150:153], v[178:181], v[60:63]
	v_mfma_f32_16x16x32_bf16 v[56:59], v[170:173], v[178:181], v[56:59]
	v_mfma_f32_16x16x32_bf16 v[44:47], v[150:153], v[186:189], v[44:47]
	v_mfma_f32_16x16x32_bf16 v[40:43], v[170:173], v[186:189], v[40:43]
	v_mfma_f32_16x16x32_bf16 v[28:31], v[150:153], v[218:221], v[28:31]
	v_mfma_f32_16x16x32_bf16 v[24:27], v[170:173], v[218:221], v[24:27]
	v_mfma_f32_16x16x32_bf16 v[12:15], v[150:153], v[226:229], v[12:15]
	v_mfma_f32_16x16x32_bf16 v[8:11], v[170:173], v[226:229], v[8:11]
	s_setprio 0
	s_barrier
	s_add_u32 s74, s58, 0x40000
	s_addc_u32 s75, s59, 0
	s_add_i32 s2, s2, s31
	s_mov_b32 m0, s2
	s_nop 0
	global_load_lds_dwordx4 v158, s[74:75]
	s_add_i32 m0, s2, 0x2000
	s_nop 0
	global_load_lds_dwordx4 v132, s[74:75]
	s_waitcnt vmcnt(6)
	s_barrier
	s_setprio 1
	v_mfma_f32_16x16x32_bf16 v[52:55], v[230:233], v[174:177], 0
	v_mfma_f32_16x16x32_bf16 v[48:51], v[238:241], v[174:177], 0
	v_mfma_f32_16x16x32_bf16 v[36:39], v[230:233], v[182:185], 0
	v_mfma_f32_16x16x32_bf16 v[32:35], v[238:241], v[182:185], 0
	v_mfma_f32_16x16x32_bf16 v[20:23], v[230:233], v[214:217], 0
	v_mfma_f32_16x16x32_bf16 v[16:19], v[238:241], v[214:217], 0
	v_mfma_f32_16x16x32_bf16 v[4:7], v[230:233], v[222:225], 0
	v_mfma_f32_16x16x32_bf16 v[0:3], v[238:241], v[222:225], 0
	v_mfma_f32_16x16x32_bf16 v[52:55], v[234:237], v[178:181], v[52:55]
	v_mfma_f32_16x16x32_bf16 v[48:51], v[242:245], v[178:181], v[48:51]
	v_mfma_f32_16x16x32_bf16 v[36:39], v[234:237], v[186:189], v[36:39]
	v_mfma_f32_16x16x32_bf16 v[32:35], v[242:245], v[186:189], v[32:35]
	v_mfma_f32_16x16x32_bf16 v[20:23], v[234:237], v[218:221], v[20:23]
	v_mfma_f32_16x16x32_bf16 v[16:19], v[242:245], v[218:221], v[16:19]
	v_mfma_f32_16x16x32_bf16 v[4:7], v[234:237], v[226:229], v[4:7]
	v_mfma_f32_16x16x32_bf16 v[0:3], v[242:245], v[226:229], v[0:3]
	s_setprio 0
	s_add_i32 s2, 0, 0x18000
	v_add_u32_e32 v140, s2, v142
	s_barrier
	ds_read_b128 v[146:149], v140
	ds_read_b128 v[150:153], v140 offset:1024
	ds_read_b128 v[166:169], v140 offset:2048
	ds_read_b128 v[170:173], v140 offset:3072
	s_add_u32 s62, s62, 0x40000
	s_addc_u32 s63, s63, 0
	s_mov_b32 m0, s48
	ds_read_b128 v[174:177], v145 offset:32768
	ds_read_b128 v[178:181], v145 offset:33792
	ds_read_b128 v[182:185], v145 offset:34816
	ds_read_b128 v[186:189], v145 offset:35840
	ds_read_b128 v[214:217], v145 offset:36864
	ds_read_b128 v[218:221], v145 offset:37888
	ds_read_b128 v[222:225], v145 offset:38912
	ds_read_b128 v[226:229], v145 offset:39936
	global_load_lds_dwordx4 v128, s[62:63]
	s_mov_b32 m0, s50
	s_nop 0
	global_load_lds_dwordx4 v130, s[62:63]
	s_waitcnt lgkmcnt(8)
	s_barrier
	s_waitcnt lgkmcnt(0)
	s_setprio 1
	s_waitcnt lgkmcnt(0)
	v_mfma_f32_16x16x32_bf16 v[124:127], v[146:149], v[174:177], v[124:127]
	v_mfma_f32_16x16x32_bf16 v[120:123], v[166:169], v[174:177], v[120:123]
	v_mfma_f32_16x16x32_bf16 v[108:111], v[146:149], v[182:185], v[108:111]
	v_mfma_f32_16x16x32_bf16 v[104:107], v[166:169], v[182:185], v[104:107]
	v_mfma_f32_16x16x32_bf16 v[92:95], v[146:149], v[214:217], v[92:95]
	v_mfma_f32_16x16x32_bf16 v[88:91], v[166:169], v[214:217], v[88:91]
	v_mfma_f32_16x16x32_bf16 v[76:79], v[146:149], v[222:225], v[76:79]
	v_mfma_f32_16x16x32_bf16 v[72:75], v[166:169], v[222:225], v[72:75]
	v_mfma_f32_16x16x32_bf16 v[124:127], v[150:153], v[178:181], v[124:127]
	v_mfma_f32_16x16x32_bf16 v[120:123], v[170:173], v[178:181], v[120:123]
	v_mfma_f32_16x16x32_bf16 v[108:111], v[150:153], v[186:189], v[108:111]
	v_mfma_f32_16x16x32_bf16 v[104:107], v[170:173], v[186:189], v[104:107]
	v_mfma_f32_16x16x32_bf16 v[92:95], v[150:153], v[218:221], v[92:95]
	v_mfma_f32_16x16x32_bf16 v[88:91], v[170:173], v[218:221], v[88:91]
	v_mfma_f32_16x16x32_bf16 v[76:79], v[150:153], v[226:229], v[76:79]
	v_mfma_f32_16x16x32_bf16 v[72:75], v[170:173], v[226:229], v[72:75]
	s_setprio 0
	s_barrier
	s_add_i32 s15, 0, 0x1c000
	s_add_i32 s2, s2, s31
	v_add_u32_e32 v140, s15, v142
	v_lshl_add_u64 v[138:139], v[138:139], 0, s[70:71]
	s_mov_b32 m0, s2
	ds_read_b128 v[230:233], v140
	ds_read_b128 v[234:237], v140 offset:1024
	ds_read_b128 v[238:241], v140 offset:2048
	ds_read_b128 v[242:245], v140 offset:3072
	global_load_lds_dwordx4 v[138:139], off
	v_lshl_add_u64 v[138:139], v[154:155], 0, s[70:71]
	s_add_i32 m0, s2, 0x2000
	s_nop 0
	global_load_lds_dwordx4 v[138:139], off
	s_barrier
	s_waitcnt lgkmcnt(0)
	s_setprio 1
	s_waitcnt lgkmcnt(0)
	v_mfma_f32_16x16x32_bf16 v[116:119], v[230:233], v[174:177], v[116:119]
	v_mfma_f32_16x16x32_bf16 v[112:115], v[238:241], v[174:177], v[112:115]
	v_mfma_f32_16x16x32_bf16 v[100:103], v[230:233], v[182:185], v[100:103]
	v_mfma_f32_16x16x32_bf16 v[96:99], v[238:241], v[182:185], v[96:99]
	v_mfma_f32_16x16x32_bf16 v[84:87], v[230:233], v[214:217], v[84:87]
	v_mfma_f32_16x16x32_bf16 v[80:83], v[238:241], v[214:217], v[80:83]
	v_mfma_f32_16x16x32_bf16 v[68:71], v[230:233], v[222:225], v[68:71]
	v_mfma_f32_16x16x32_bf16 v[64:67], v[238:241], v[222:225], v[64:67]
	v_mfma_f32_16x16x32_bf16 v[116:119], v[234:237], v[178:181], v[116:119]
	v_mfma_f32_16x16x32_bf16 v[112:115], v[242:245], v[178:181], v[112:115]
	v_mfma_f32_16x16x32_bf16 v[100:103], v[234:237], v[186:189], v[100:103]
	v_mfma_f32_16x16x32_bf16 v[96:99], v[242:245], v[186:189], v[96:99]
	v_mfma_f32_16x16x32_bf16 v[84:87], v[234:237], v[218:221], v[84:87]
	v_mfma_f32_16x16x32_bf16 v[80:83], v[242:245], v[218:221], v[80:83]
	v_mfma_f32_16x16x32_bf16 v[68:71], v[234:237], v[226:229], v[68:71]
	v_mfma_f32_16x16x32_bf16 v[64:67], v[242:245], v[226:229], v[64:67]
	s_setprio 0
	s_mov_b32 m0, s51
	v_lshl_add_u64 v[138:139], v[190:191], 0, s[70:71]
	s_barrier
	ds_read_b128 v[174:177], v145 offset:49152
	ds_read_b128 v[178:181], v145 offset:50176
	ds_read_b128 v[182:185], v145 offset:51200
	ds_read_b128 v[186:189], v145 offset:52224
	ds_read_b128 v[214:217], v145 offset:53248
	ds_read_b128 v[218:221], v145 offset:54272
	ds_read_b128 v[222:225], v145 offset:55296
	ds_read_b128 v[226:229], v145 offset:56320
	global_load_lds_dwordx4 v[138:139], off
	v_lshl_add_u64 v[138:139], v[202:203], 0, s[70:71]
	s_mov_b32 m0, s65
	s_nop 0
	global_load_lds_dwordx4 v[138:139], off
	s_barrier
	s_waitcnt lgkmcnt(0)
	s_setprio 1
	s_waitcnt lgkmcnt(0)
	v_mfma_f32_16x16x32_bf16 v[60:63], v[146:149], v[174:177], v[60:63]
	v_mfma_f32_16x16x32_bf16 v[56:59], v[166:169], v[174:177], v[56:59]
	v_mfma_f32_16x16x32_bf16 v[44:47], v[146:149], v[182:185], v[44:47]
	v_mfma_f32_16x16x32_bf16 v[40:43], v[166:169], v[182:185], v[40:43]
	v_mfma_f32_16x16x32_bf16 v[28:31], v[146:149], v[214:217], v[28:31]
	v_mfma_f32_16x16x32_bf16 v[24:27], v[166:169], v[214:217], v[24:27]
	v_mfma_f32_16x16x32_bf16 v[12:15], v[146:149], v[222:225], v[12:15]
	v_mfma_f32_16x16x32_bf16 v[8:11], v[166:169], v[222:225], v[8:11]
	v_mfma_f32_16x16x32_bf16 v[60:63], v[150:153], v[178:181], v[60:63]
	v_mfma_f32_16x16x32_bf16 v[56:59], v[170:173], v[178:181], v[56:59]
	v_mfma_f32_16x16x32_bf16 v[44:47], v[150:153], v[186:189], v[44:47]
	v_mfma_f32_16x16x32_bf16 v[40:43], v[170:173], v[186:189], v[40:43]
	v_mfma_f32_16x16x32_bf16 v[28:31], v[150:153], v[218:221], v[28:31]
	v_mfma_f32_16x16x32_bf16 v[24:27], v[170:173], v[218:221], v[24:27]
	v_mfma_f32_16x16x32_bf16 v[12:15], v[150:153], v[226:229], v[12:15]
	v_mfma_f32_16x16x32_bf16 v[8:11], v[170:173], v[226:229], v[8:11]
	s_setprio 0
	s_barrier
	s_add_u32 s58, s58, 0x40080
	s_addc_u32 s59, s59, 0
	s_add_i32 s2, s15, s31
	s_mov_b32 m0, s2
	s_nop 0
	global_load_lds_dwordx4 v158, s[58:59]
	s_add_i32 m0, s2, 0x2000
	s_nop 0
	global_load_lds_dwordx4 v132, s[58:59]
	s_waitcnt vmcnt(6)
	s_barrier
	s_setprio 1
	v_mfma_f32_16x16x32_bf16 v[52:55], v[230:233], v[174:177], v[52:55]
	v_mfma_f32_16x16x32_bf16 v[48:51], v[238:241], v[174:177], v[48:51]
	v_mfma_f32_16x16x32_bf16 v[36:39], v[230:233], v[182:185], v[36:39]
	v_mfma_f32_16x16x32_bf16 v[32:35], v[238:241], v[182:185], v[32:35]
	v_mfma_f32_16x16x32_bf16 v[20:23], v[230:233], v[214:217], v[20:23]
	v_mfma_f32_16x16x32_bf16 v[16:19], v[238:241], v[214:217], v[16:19]
	v_mfma_f32_16x16x32_bf16 v[4:7], v[230:233], v[222:225], v[4:7]
	v_mfma_f32_16x16x32_bf16 v[0:3], v[238:241], v[222:225], v[0:3]
	v_mfma_f32_16x16x32_bf16 v[52:55], v[234:237], v[178:181], v[52:55]
	v_mfma_f32_16x16x32_bf16 v[48:51], v[242:245], v[178:181], v[48:51]
	v_mfma_f32_16x16x32_bf16 v[36:39], v[234:237], v[186:189], v[36:39]
	v_mfma_f32_16x16x32_bf16 v[32:35], v[242:245], v[186:189], v[32:35]
	v_mfma_f32_16x16x32_bf16 v[20:23], v[234:237], v[218:221], v[20:23]
	v_mfma_f32_16x16x32_bf16 v[16:19], v[242:245], v[218:221], v[16:19]
	v_mfma_f32_16x16x32_bf16 v[4:7], v[234:237], v[226:229], v[4:7]
	v_mfma_f32_16x16x32_bf16 v[0:3], v[242:245], v[226:229], v[0:3]
	s_setprio 0
	s_add_i32 s72, s72, 2
	s_add_u32 s24, s24, 0x100
	s_addc_u32 s25, s25, 0
	s_add_u32 s68, s68, 0x100
	s_addc_u32 s69, s69, 0
	s_cmp_gt_u32 s72, 13
	s_barrier
	s_cbranch_scc1 .Lzp_exit2
.LBB0_534:
	s_add_u32 s2, s24, 0xfffc0080
	s_addc_u32 s15, s25, -1
	s_add_i32 s73, 0, 0x10000
	v_add_u32_e32 v138, s73, v142
	ds_read_b128 v[146:149], v138
	ds_read_b128 v[150:153], v138 offset:1024
	ds_read_b128 v[166:169], v138 offset:2048
	ds_read_b128 v[170:173], v138 offset:3072
	s_cmp_eq_u32 s72, 12
	s_cselect_b32 s63, s9, s15
	s_cselect_b32 s62, s17, s2
	s_cselect_b32 s59, s11, s69
	s_cselect_b32 s58, s23, s68
	s_add_i32 m0, s43, 0xc000
	ds_read_b128 v[174:177], v145
	ds_read_b128 v[178:181], v145 offset:1024
	ds_read_b128 v[182:185], v145 offset:2048
	ds_read_b128 v[186:189], v145 offset:3072
	ds_read_b128 v[214:217], v145 offset:4096
	ds_read_b128 v[218:221], v145 offset:5120
	ds_read_b128 v[222:225], v145 offset:6144
	ds_read_b128 v[226:229], v145 offset:7168
	global_load_lds_dwordx4 v134, s[24:25]
	s_add_i32 m0, s43, 0xe000
	s_nop 0
	global_load_lds_dwordx4 v136, s[24:25]
	s_waitcnt lgkmcnt(8)
	s_barrier
	s_waitcnt lgkmcnt(0)
	s_setprio 1
	s_waitcnt lgkmcnt(0)
	v_mfma_f32_16x16x32_bf16 v[124:127], v[146:149], v[174:177], v[124:127]
	v_mfma_f32_16x16x32_bf16 v[120:123], v[166:169], v[174:177], v[120:123]
	v_mfma_f32_16x16x32_bf16 v[108:111], v[146:149], v[182:185], v[108:111]
	v_mfma_f32_16x16x32_bf16 v[104:107], v[166:169], v[182:185], v[104:107]
	v_mfma_f32_16x16x32_bf16 v[92:95], v[146:149], v[214:217], v[92:95]
	v_mfma_f32_16x16x32_bf16 v[88:91], v[166:169], v[214:217], v[88:91]
	v_mfma_f32_16x16x32_bf16 v[76:79], v[146:149], v[222:225], v[76:79]
	v_mfma_f32_16x16x32_bf16 v[72:75], v[166:169], v[222:225], v[72:75]
	v_mfma_f32_16x16x32_bf16 v[124:127], v[150:153], v[178:181], v[124:127]
	v_mfma_f32_16x16x32_bf16 v[120:123], v[170:173], v[178:181], v[120:123]
	v_mfma_f32_16x16x32_bf16 v[108:111], v[150:153], v[186:189], v[108:111]
	v_mfma_f32_16x16x32_bf16 v[104:107], v[170:173], v[186:189], v[104:107]
	v_mfma_f32_16x16x32_bf16 v[92:95], v[150:153], v[218:221], v[92:95]
	v_mfma_f32_16x16x32_bf16 v[88:91], v[170:173], v[218:221], v[88:91]
	v_mfma_f32_16x16x32_bf16 v[76:79], v[150:153], v[226:229], v[76:79]
	v_mfma_f32_16x16x32_bf16 v[72:75], v[170:173], v[226:229], v[72:75]
	s_setprio 0
	s_barrier
	s_add_i32 s2, 0, 0x14000
	v_add_u32_e32 v138, s2, v142
	s_add_i32 s15, s73, s31
	ds_read_b128 v[230:233], v138
	ds_read_b128 v[234:237], v138 offset:1024
	ds_read_b128 v[238:241], v138 offset:2048
	ds_read_b128 v[242:245], v138 offset:3072
	v_lshl_add_u64 v[138:139], s[58:59], 0, v[158:159]
	s_mov_b32 m0, s15
	v_lshl_add_u64 v[154:155], s[58:59], 0, v[132:133]
	global_load_lds_dwordx4 v158, s[58:59]
	s_add_i32 m0, s15, 0x2000
	s_nop 0
	global_load_lds_dwordx4 v132, s[58:59]
	s_barrier
	s_waitcnt lgkmcnt(0)
	s_setprio 1
	s_waitcnt lgkmcnt(0)
	v_mfma_f32_16x16x32_bf16 v[116:119], v[230:233], v[174:177], v[116:119]
	v_mfma_f32_16x16x32_bf16 v[112:115], v[238:241], v[174:177], v[112:115]
	v_mfma_f32_16x16x32_bf16 v[100:103], v[230:233], v[182:185], v[100:103]
	v_mfma_f32_16x16x32_bf16 v[96:99], v[238:241], v[182:185], v[96:99]
	v_mfma_f32_16x16x32_bf16 v[84:87], v[230:233], v[214:217], v[84:87]
	v_mfma_f32_16x16x32_bf16 v[80:83], v[238:241], v[214:217], v[80:83]
	v_mfma_f32_16x16x32_bf16 v[68:71], v[230:233], v[222:225], v[68:71]
	v_mfma_f32_16x16x32_bf16 v[64:67], v[238:241], v[222:225], v[64:67]
	v_mfma_f32_16x16x32_bf16 v[116:119], v[234:237], v[178:181], v[116:119]
	v_mfma_f32_16x16x32_bf16 v[112:115], v[242:245], v[178:181], v[112:115]
	v_mfma_f32_16x16x32_bf16 v[100:103], v[234:237], v[186:189], v[100:103]
	v_mfma_f32_16x16x32_bf16 v[96:99], v[242:245], v[186:189], v[96:99]
	v_mfma_f32_16x16x32_bf16 v[84:87], v[234:237], v[218:221], v[84:87]
	v_mfma_f32_16x16x32_bf16 v[80:83], v[242:245], v[218:221], v[80:83]
	v_mfma_f32_16x16x32_bf16 v[68:71], v[234:237], v[226:229], v[68:71]
	v_mfma_f32_16x16x32_bf16 v[64:67], v[242:245], v[226:229], v[64:67]
	s_setprio 0
	s_mov_b32 m0, s43
	v_lshl_add_u64 v[190:191], s[62:63], 0, v[128:129]
	s_barrier
	ds_read_b128 v[174:177], v145 offset:16384
	ds_read_b128 v[178:181], v145 offset:17408
	ds_read_b128 v[182:185], v145 offset:18432
	ds_read_b128 v[186:189], v145 offset:19456
	ds_read_b128 v[214:217], v145 offset:20480
	ds_read_b128 v[218:221], v145 offset:21504
	ds_read_b128 v[222:225], v145 offset:22528
	ds_read_b128 v[226:229], v145 offset:23552
	global_load_lds_dwordx4 v128, s[62:63]
	v_lshl_add_u64 v[202:203], s[62:63], 0, v[130:131]
	s_mov_b32 m0, s47
	s_nop 0
	global_load_lds_dwordx4 v130, s[62:63]
	s_barrier
	s_waitcnt lgkmcnt(0)
	s_setprio 1
	s_waitcnt lgkmcnt(0)
	v_mfma_f32_16x16x32_bf16 v[60:63], v[146:149], v[174:177], v[60:63]
	v_mfma_f32_16x16x32_bf16 v[56:59], v[166:169], v[174:177], v[56:59]
	v_mfma_f32_16x16x32_bf16 v[44:47], v[146:149], v[182:185], v[44:47]
	v_mfma_f32_16x16x32_bf16 v[40:43], v[166:169], v[182:185], v[40:43]
	v_mfma_f32_16x16x32_bf16 v[28:31], v[146:149], v[214:217], v[28:31]
	v_mfma_f32_16x16x32_bf16 v[24:27], v[166:169], v[214:217], v[24:27]
	v_mfma_f32_16x16x32_bf16 v[12:15], v[146:149], v[222:225], v[12:15]
	v_mfma_f32_16x16x32_bf16 v[8:11], v[166:169], v[222:225], v[8:11]
	v_mfma_f32_16x16x32_bf16 v[60:63], v[150:153], v[178:181], v[60:63]
	v_mfma_f32_16x16x32_bf16 v[56:59], v[170:173], v[178:181], v[56:59]
	v_mfma_f32_16x16x32_bf16 v[44:47], v[150:153], v[186:189], v[44:47]
	v_mfma_f32_16x16x32_bf16 v[40:43], v[170:173], v[186:189], v[40:43]
	v_mfma_f32_16x16x32_bf16 v[28:31], v[150:153], v[218:221], v[28:31]
	v_mfma_f32_16x16x32_bf16 v[24:27], v[170:173], v[218:221], v[24:27]
	v_mfma_f32_16x16x32_bf16 v[12:15], v[150:153], v[226:229], v[12:15]
	v_mfma_f32_16x16x32_bf16 v[8:11], v[170:173], v[226:229], v[8:11]
	s_setprio 0
	s_barrier
	s_add_u32 s74, s58, 0x40000
	s_addc_u32 s75, s59, 0
	s_add_i32 s2, s2, s31
	s_mov_b32 m0, s2
	s_nop 0
	global_load_lds_dwordx4 v158, s[74:75]
	s_add_i32 m0, s2, 0x2000
	s_nop 0
	global_load_lds_dwordx4 v132, s[74:75]
	s_waitcnt vmcnt(6)
	s_barrier
	s_setprio 1
	v_mfma_f32_16x16x32_bf16 v[52:55], v[230:233], v[174:177], v[52:55]
	v_mfma_f32_16x16x32_bf16 v[48:51], v[238:241], v[174:177], v[48:51]
	v_mfma_f32_16x16x32_bf16 v[36:39], v[230:233], v[182:185], v[36:39]
	v_mfma_f32_16x16x32_bf16 v[32:35], v[238:241], v[182:185], v[32:35]
	v_mfma_f32_16x16x32_bf16 v[20:23], v[230:233], v[214:217], v[20:23]
	v_mfma_f32_16x16x32_bf16 v[16:19], v[238:241], v[214:217], v[16:19]
	v_mfma_f32_16x16x32_bf16 v[4:7], v[230:233], v[222:225], v[4:7]
	v_mfma_f32_16x16x32_bf16 v[0:3], v[238:241], v[222:225], v[0:3]
	v_mfma_f32_16x16x32_bf16 v[52:55], v[234:237], v[178:181], v[52:55]
	v_mfma_f32_16x16x32_bf16 v[48:51], v[242:245], v[178:181], v[48:51]
	v_mfma_f32_16x16x32_bf16 v[36:39], v[234:237], v[186:189], v[36:39]
	v_mfma_f32_16x16x32_bf16 v[32:35], v[242:245], v[186:189], v[32:35]
	v_mfma_f32_16x16x32_bf16 v[20:23], v[234:237], v[218:221], v[20:23]
	v_mfma_f32_16x16x32_bf16 v[16:19], v[242:245], v[218:221], v[16:19]
	v_mfma_f32_16x16x32_bf16 v[4:7], v[234:237], v[226:229], v[4:7]
	v_mfma_f32_16x16x32_bf16 v[0:3], v[242:245], v[226:229], v[0:3]
	s_setprio 0
	s_add_i32 s2, 0, 0x18000
	v_add_u32_e32 v140, s2, v142
	s_barrier
	ds_read_b128 v[146:149], v140
	ds_read_b128 v[150:153], v140 offset:1024
	ds_read_b128 v[166:169], v140 offset:2048
	ds_read_b128 v[170:173], v140 offset:3072
	s_add_u32 s62, s62, 0x40000
	s_addc_u32 s63, s63, 0
	s_mov_b32 m0, s48
	ds_read_b128 v[174:177], v145 offset:32768
	ds_read_b128 v[178:181], v145 offset:33792
	ds_read_b128 v[182:185], v145 offset:34816
	ds_read_b128 v[186:189], v145 offset:35840
	ds_read_b128 v[214:217], v145 offset:36864
	ds_read_b128 v[218:221], v145 offset:37888
	ds_read_b128 v[222:225], v145 offset:38912
	ds_read_b128 v[226:229], v145 offset:39936
	global_load_lds_dwordx4 v128, s[62:63]
	s_mov_b32 m0, s50
	s_nop 0
	global_load_lds_dwordx4 v130, s[62:63]
	s_waitcnt lgkmcnt(8)
	s_barrier
	s_waitcnt lgkmcnt(0)
	s_setprio 1
	s_waitcnt lgkmcnt(0)
	v_mfma_f32_16x16x32_bf16 v[124:127], v[146:149], v[174:177], v[124:127]
	v_mfma_f32_16x16x32_bf16 v[120:123], v[166:169], v[174:177], v[120:123]
	v_mfma_f32_16x16x32_bf16 v[108:111], v[146:149], v[182:185], v[108:111]
	v_mfma_f32_16x16x32_bf16 v[104:107], v[166:169], v[182:185], v[104:107]
	v_mfma_f32_16x16x32_bf16 v[92:95], v[146:149], v[214:217], v[92:95]
	v_mfma_f32_16x16x32_bf16 v[88:91], v[166:169], v[214:217], v[88:91]
	v_mfma_f32_16x16x32_bf16 v[76:79], v[146:149], v[222:225], v[76:79]
	v_mfma_f32_16x16x32_bf16 v[72:75], v[166:169], v[222:225], v[72:75]
	v_mfma_f32_16x16x32_bf16 v[124:127], v[150:153], v[178:181], v[124:127]
	v_mfma_f32_16x16x32_bf16 v[120:123], v[170:173], v[178:181], v[120:123]
	v_mfma_f32_16x16x32_bf16 v[108:111], v[150:153], v[186:189], v[108:111]
	v_mfma_f32_16x16x32_bf16 v[104:107], v[170:173], v[186:189], v[104:107]
	v_mfma_f32_16x16x32_bf16 v[92:95], v[150:153], v[218:221], v[92:95]
	v_mfma_f32_16x16x32_bf16 v[88:91], v[170:173], v[218:221], v[88:91]
	v_mfma_f32_16x16x32_bf16 v[76:79], v[150:153], v[226:229], v[76:79]
	v_mfma_f32_16x16x32_bf16 v[72:75], v[170:173], v[226:229], v[72:75]
	s_setprio 0
	s_barrier
	s_add_i32 s15, 0, 0x1c000
	s_add_i32 s2, s2, s31
	v_add_u32_e32 v140, s15, v142
	v_lshl_add_u64 v[138:139], v[138:139], 0, s[70:71]
	s_mov_b32 m0, s2
	ds_read_b128 v[230:233], v140
	ds_read_b128 v[234:237], v140 offset:1024
	ds_read_b128 v[238:241], v140 offset:2048
	ds_read_b128 v[242:245], v140 offset:3072
	global_load_lds_dwordx4 v[138:139], off
	v_lshl_add_u64 v[138:139], v[154:155], 0, s[70:71]
	s_add_i32 m0, s2, 0x2000
	s_nop 0
	global_load_lds_dwordx4 v[138:139], off
	s_barrier
	s_waitcnt lgkmcnt(0)
	s_setprio 1
	s_waitcnt lgkmcnt(0)
	v_mfma_f32_16x16x32_bf16 v[116:119], v[230:233], v[174:177], v[116:119]
	v_mfma_f32_16x16x32_bf16 v[112:115], v[238:241], v[174:177], v[112:115]
	v_mfma_f32_16x16x32_bf16 v[100:103], v[230:233], v[182:185], v[100:103]
	v_mfma_f32_16x16x32_bf16 v[96:99], v[238:241], v[182:185], v[96:99]
	v_mfma_f32_16x16x32_bf16 v[84:87], v[230:233], v[214:217], v[84:87]
	v_mfma_f32_16x16x32_bf16 v[80:83], v[238:241], v[214:217], v[80:83]
	v_mfma_f32_16x16x32_bf16 v[68:71], v[230:233], v[222:225], v[68:71]
	v_mfma_f32_16x16x32_bf16 v[64:67], v[238:241], v[222:225], v[64:67]
	v_mfma_f32_16x16x32_bf16 v[116:119], v[234:237], v[178:181], v[116:119]
	v_mfma_f32_16x16x32_bf16 v[112:115], v[242:245], v[178:181], v[112:115]
	v_mfma_f32_16x16x32_bf16 v[100:103], v[234:237], v[186:189], v[100:103]
	v_mfma_f32_16x16x32_bf16 v[96:99], v[242:245], v[186:189], v[96:99]
	v_mfma_f32_16x16x32_bf16 v[84:87], v[234:237], v[218:221], v[84:87]
	v_mfma_f32_16x16x32_bf16 v[80:83], v[242:245], v[218:221], v[80:83]
	v_mfma_f32_16x16x32_bf16 v[68:71], v[234:237], v[226:229], v[68:71]
	v_mfma_f32_16x16x32_bf16 v[64:67], v[242:245], v[226:229], v[64:67]
	s_setprio 0
	s_mov_b32 m0, s51
	v_lshl_add_u64 v[138:139], v[190:191], 0, s[70:71]
	s_barrier
	ds_read_b128 v[174:177], v145 offset:49152
	ds_read_b128 v[178:181], v145 offset:50176
	ds_read_b128 v[182:185], v145 offset:51200
	ds_read_b128 v[186:189], v145 offset:52224
	ds_read_b128 v[214:217], v145 offset:53248
	ds_read_b128 v[218:221], v145 offset:54272
	ds_read_b128 v[222:225], v145 offset:55296
	ds_read_b128 v[226:229], v145 offset:56320
	global_load_lds_dwordx4 v[138:139], off
	v_lshl_add_u64 v[138:139], v[202:203], 0, s[70:71]
	s_mov_b32 m0, s65
	s_nop 0
	global_load_lds_dwordx4 v[138:139], off
	s_barrier
	s_waitcnt lgkmcnt(0)
	s_setprio 1
	s_waitcnt lgkmcnt(0)
	v_mfma_f32_16x16x32_bf16 v[60:63], v[146:149], v[174:177], v[60:63]
	v_mfma_f32_16x16x32_bf16 v[56:59], v[166:169], v[174:177], v[56:59]
	v_mfma_f32_16x16x32_bf16 v[44:47], v[146:149], v[182:185], v[44:47]
	v_mfma_f32_16x16x32_bf16 v[40:43], v[166:169], v[182:185], v[40:43]
	v_mfma_f32_16x16x32_bf16 v[28:31], v[146:149], v[214:217], v[28:31]
	v_mfma_f32_16x16x32_bf16 v[24:27], v[166:169], v[214:217], v[24:27]
	v_mfma_f32_16x16x32_bf16 v[12:15], v[146:149], v[222:225], v[12:15]
	v_mfma_f32_16x16x32_bf16 v[8:11], v[166:169], v[222:225], v[8:11]
	v_mfma_f32_16x16x32_bf16 v[60:63], v[150:153], v[178:181], v[60:63]
	v_mfma_f32_16x16x32_bf16 v[56:59], v[170:173], v[178:181], v[56:59]
	v_mfma_f32_16x16x32_bf16 v[44:47], v[150:153], v[186:189], v[44:47]
	v_mfma_f32_16x16x32_bf16 v[40:43], v[170:173], v[186:189], v[40:43]
	v_mfma_f32_16x16x32_bf16 v[28:31], v[150:153], v[218:221], v[28:31]
	v_mfma_f32_16x16x32_bf16 v[24:27], v[170:173], v[218:221], v[24:27]
	v_mfma_f32_16x16x32_bf16 v[12:15], v[150:153], v[226:229], v[12:15]
	v_mfma_f32_16x16x32_bf16 v[8:11], v[170:173], v[226:229], v[8:11]
	s_setprio 0
	s_barrier
	s_add_u32 s58, s58, 0x40080
	s_addc_u32 s59, s59, 0
	s_add_i32 s2, s15, s31
	s_mov_b32 m0, s2
	s_nop 0
	global_load_lds_dwordx4 v158, s[58:59]
	s_add_i32 m0, s2, 0x2000
	s_nop 0
	global_load_lds_dwordx4 v132, s[58:59]
	s_waitcnt vmcnt(6)
	s_barrier
	s_setprio 1
	v_mfma_f32_16x16x32_bf16 v[52:55], v[230:233], v[174:177], v[52:55]
	v_mfma_f32_16x16x32_bf16 v[48:51], v[238:241], v[174:177], v[48:51]
	v_mfma_f32_16x16x32_bf16 v[36:39], v[230:233], v[182:185], v[36:39]
	v_mfma_f32_16x16x32_bf16 v[32:35], v[238:241], v[182:185], v[32:35]
	v_mfma_f32_16x16x32_bf16 v[20:23], v[230:233], v[214:217], v[20:23]
	v_mfma_f32_16x16x32_bf16 v[16:19], v[238:241], v[214:217], v[16:19]
	v_mfma_f32_16x16x32_bf16 v[4:7], v[230:233], v[222:225], v[4:7]
	v_mfma_f32_16x16x32_bf16 v[0:3], v[238:241], v[222:225], v[0:3]
	v_mfma_f32_16x16x32_bf16 v[52:55], v[234:237], v[178:181], v[52:55]
	v_mfma_f32_16x16x32_bf16 v[48:51], v[242:245], v[178:181], v[48:51]
	v_mfma_f32_16x16x32_bf16 v[36:39], v[234:237], v[186:189], v[36:39]
	v_mfma_f32_16x16x32_bf16 v[32:35], v[242:245], v[186:189], v[32:35]
	v_mfma_f32_16x16x32_bf16 v[20:23], v[234:237], v[218:221], v[20:23]
	v_mfma_f32_16x16x32_bf16 v[16:19], v[242:245], v[218:221], v[16:19]
	v_mfma_f32_16x16x32_bf16 v[4:7], v[234:237], v[226:229], v[4:7]
	v_mfma_f32_16x16x32_bf16 v[0:3], v[242:245], v[226:229], v[0:3]
	s_setprio 0
	s_add_i32 s72, s72, 2
	s_add_u32 s24, s24, 0x100
	s_addc_u32 s25, s25, 0
	s_add_u32 s68, s68, 0x100
	s_addc_u32 s69, s69, 0
	s_cmp_gt_u32 s72, 13
	s_barrier
	s_cbranch_scc0 .LBB0_534

.LBB0_605:
	s_add_i32 vcc_hi, s12, 2
	s_add_u32 s66, s10, 0x80
	s_addc_u32 s13, s11, 0
	s_add_i32 s2, 0, 0x10000
	v_add_u32_e32 v154, s2, v147
	ds_read_b128 v[142:145], v154
	ds_read_b128 v[150:153], v154 offset:1024
	ds_read_b128 v[166:169], v154 offset:2048
	ds_read_b128 v[170:173], v154 offset:3072
	s_cmp_eq_u32 s81, s12
	s_cselect_b32 s12, s62, s66
	s_cselect_b32 s13, s63, s13
	s_cselect_b32 s67, s75, vcc_lo
	s_cselect_b32 s66, s74, s73
	s_add_i32 m0, s68, 0xc000
	ds_read_b128 v[174:177], v149
	ds_read_b128 v[178:181], v149 offset:1024
	ds_read_b128 v[182:185], v149 offset:2048
	ds_read_b128 v[186:189], v149 offset:3072
	ds_read_b128 v[214:217], v149 offset:4096
	ds_read_b128 v[218:221], v149 offset:5120
	ds_read_b128 v[222:225], v149 offset:6144
	ds_read_b128 v[226:229], v149 offset:7168
	global_load_lds_dwordx4 v138, s[10:11]
	s_add_i32 m0, s68, 0xe000
	s_nop 0
	global_load_lds_dwordx4 v140, s[10:11]
	s_waitcnt lgkmcnt(8)
	s_barrier
	s_waitcnt lgkmcnt(0)
	s_setprio 1
	s_waitcnt lgkmcnt(0)
	v_mfma_f32_16x16x32_bf16 v[124:127], v[142:145], v[174:177], v[124:127]
	v_mfma_f32_16x16x32_bf16 v[120:123], v[166:169], v[174:177], v[120:123]
	v_mfma_f32_16x16x32_bf16 v[108:111], v[142:145], v[182:185], v[108:111]
	v_mfma_f32_16x16x32_bf16 v[104:107], v[166:169], v[182:185], v[104:107]
	v_mfma_f32_16x16x32_bf16 v[92:95], v[142:145], v[214:217], v[92:95]
	v_mfma_f32_16x16x32_bf16 v[88:91], v[166:169], v[214:217], v[88:91]
	v_mfma_f32_16x16x32_bf16 v[76:79], v[142:145], v[222:225], v[76:79]
	v_mfma_f32_16x16x32_bf16 v[72:75], v[166:169], v[222:225], v[72:75]
	v_mfma_f32_16x16x32_bf16 v[124:127], v[150:153], v[178:181], v[124:127]
	v_mfma_f32_16x16x32_bf16 v[120:123], v[170:173], v[178:181], v[120:123]
	v_mfma_f32_16x16x32_bf16 v[108:111], v[150:153], v[186:189], v[108:111]
	v_mfma_f32_16x16x32_bf16 v[104:107], v[170:173], v[186:189], v[104:107]
	v_mfma_f32_16x16x32_bf16 v[92:95], v[150:153], v[218:221], v[92:95]
	v_mfma_f32_16x16x32_bf16 v[88:91], v[170:173], v[218:221], v[88:91]
	v_mfma_f32_16x16x32_bf16 v[76:79], v[150:153], v[226:229], v[76:79]
	v_mfma_f32_16x16x32_bf16 v[72:75], v[170:173], v[226:229], v[72:75]
	s_setprio 0
	s_barrier
	s_add_i32 s15, 0, 0x14000
	v_add_u32_e32 v154, s15, v147
	s_add_i32 s2, s2, s0
	ds_read_b128 v[230:233], v154
	ds_read_b128 v[234:237], v154 offset:1024
	ds_read_b128 v[238:241], v154 offset:2048
	ds_read_b128 v[242:245], v154 offset:3072
	v_lshl_add_u64 v[154:155], s[66:67], 0, v[130:131]
	s_mov_b32 m0, s2
	v_lshl_add_u64 v[190:191], s[66:67], 0, v[134:135]
	global_load_lds_dwordx4 v130, s[66:67]
	s_add_i32 m0, s2, 0x2000
	s_nop 0
	global_load_lds_dwordx4 v134, s[66:67]
	s_barrier
	s_waitcnt lgkmcnt(0)
	s_setprio 1
	s_waitcnt lgkmcnt(0)
	v_mfma_f32_16x16x32_bf16 v[116:119], v[230:233], v[174:177], v[116:119]
	v_mfma_f32_16x16x32_bf16 v[112:115], v[238:241], v[174:177], v[112:115]
	v_mfma_f32_16x16x32_bf16 v[100:103], v[230:233], v[182:185], v[100:103]
	v_mfma_f32_16x16x32_bf16 v[96:99], v[238:241], v[182:185], v[96:99]
	v_mfma_f32_16x16x32_bf16 v[84:87], v[230:233], v[214:217], v[84:87]
	v_mfma_f32_16x16x32_bf16 v[80:83], v[238:241], v[214:217], v[80:83]
	v_mfma_f32_16x16x32_bf16 v[68:71], v[230:233], v[222:225], v[68:71]
	v_mfma_f32_16x16x32_bf16 v[64:67], v[238:241], v[222:225], v[64:67]
	v_mfma_f32_16x16x32_bf16 v[116:119], v[234:237], v[178:181], v[116:119]
	v_mfma_f32_16x16x32_bf16 v[112:115], v[242:245], v[178:181], v[112:115]
	v_mfma_f32_16x16x32_bf16 v[100:103], v[234:237], v[186:189], v[100:103]
	v_mfma_f32_16x16x32_bf16 v[96:99], v[242:245], v[186:189], v[96:99]
	v_mfma_f32_16x16x32_bf16 v[84:87], v[234:237], v[218:221], v[84:87]
	v_mfma_f32_16x16x32_bf16 v[80:83], v[242:245], v[218:221], v[80:83]
	v_mfma_f32_16x16x32_bf16 v[68:71], v[234:237], v[226:229], v[68:71]
	v_mfma_f32_16x16x32_bf16 v[64:67], v[242:245], v[226:229], v[64:67]
	s_setprio 0
	s_mov_b32 m0, s68
	v_lshl_add_u64 v[202:203], s[12:13], 0, v[128:129]
	s_barrier
	ds_read_b128 v[174:177], v149 offset:16384
	ds_read_b128 v[178:181], v149 offset:17408
	ds_read_b128 v[182:185], v149 offset:18432
	ds_read_b128 v[186:189], v149 offset:19456
	ds_read_b128 v[214:217], v149 offset:20480
	ds_read_b128 v[218:221], v149 offset:21504
	ds_read_b128 v[222:225], v149 offset:22528
	ds_read_b128 v[226:229], v149 offset:23552
	global_load_lds_dwordx4 v128, s[12:13]
	v_lshl_add_u64 v[204:205], s[12:13], 0, v[132:133]
	s_mov_b32 m0, s69
	s_nop 0
	global_load_lds_dwordx4 v132, s[12:13]
	s_barrier
	s_waitcnt lgkmcnt(0)
	s_setprio 1
	s_waitcnt lgkmcnt(0)
	v_mfma_f32_16x16x32_bf16 v[60:63], v[142:145], v[174:177], v[60:63]
	v_mfma_f32_16x16x32_bf16 v[56:59], v[166:169], v[174:177], v[56:59]
	v_mfma_f32_16x16x32_bf16 v[44:47], v[142:145], v[182:185], v[44:47]
	v_mfma_f32_16x16x32_bf16 v[40:43], v[166:169], v[182:185], v[40:43]
	v_mfma_f32_16x16x32_bf16 v[28:31], v[142:145], v[214:217], v[28:31]
	v_mfma_f32_16x16x32_bf16 v[24:27], v[166:169], v[214:217], v[24:27]
	v_mfma_f32_16x16x32_bf16 v[12:15], v[142:145], v[222:225], v[12:15]
	v_mfma_f32_16x16x32_bf16 v[8:11], v[166:169], v[222:225], v[8:11]
	v_mfma_f32_16x16x32_bf16 v[60:63], v[150:153], v[178:181], v[60:63]
	v_mfma_f32_16x16x32_bf16 v[56:59], v[170:173], v[178:181], v[56:59]
	v_mfma_f32_16x16x32_bf16 v[44:47], v[150:153], v[186:189], v[44:47]
	v_mfma_f32_16x16x32_bf16 v[40:43], v[170:173], v[186:189], v[40:43]
	v_mfma_f32_16x16x32_bf16 v[28:31], v[150:153], v[218:221], v[28:31]
	v_mfma_f32_16x16x32_bf16 v[24:27], v[170:173], v[218:221], v[24:27]
	v_mfma_f32_16x16x32_bf16 v[12:15], v[150:153], v[226:229], v[12:15]
	v_mfma_f32_16x16x32_bf16 v[8:11], v[170:173], v[226:229], v[8:11]
	s_setprio 0
	s_barrier
	s_add_u32 s66, s66, s35
	s_addc_u32 s67, s67, 0
	s_add_i32 s2, s15, s0
	v_lshl_add_u64 v[246:247], s[66:67], 0, v[130:131]
	s_mov_b32 m0, s2
	v_lshl_add_u64 v[248:249], s[66:67], 0, v[134:135]
	global_load_lds_dwordx4 v130, s[66:67]
	s_add_i32 m0, s2, 0x2000
	s_nop 0
	global_load_lds_dwordx4 v134, s[66:67]
	s_waitcnt vmcnt(6)
	s_barrier
	s_setprio 1
	v_mfma_f32_16x16x32_bf16 v[52:55], v[230:233], v[174:177], v[52:55]
	v_mfma_f32_16x16x32_bf16 v[48:51], v[238:241], v[174:177], v[48:51]
	v_mfma_f32_16x16x32_bf16 v[36:39], v[230:233], v[182:185], v[36:39]
	v_mfma_f32_16x16x32_bf16 v[32:35], v[238:241], v[182:185], v[32:35]
	v_mfma_f32_16x16x32_bf16 v[20:23], v[230:233], v[214:217], v[20:23]
	v_mfma_f32_16x16x32_bf16 v[16:19], v[238:241], v[214:217], v[16:19]
	v_mfma_f32_16x16x32_bf16 v[4:7], v[230:233], v[222:225], v[4:7]
	v_mfma_f32_16x16x32_bf16 v[0:3], v[238:241], v[222:225], v[0:3]
	v_mfma_f32_16x16x32_bf16 v[52:55], v[234:237], v[178:181], v[52:55]
	v_mfma_f32_16x16x32_bf16 v[48:51], v[242:245], v[178:181], v[48:51]
	v_mfma_f32_16x16x32_bf16 v[36:39], v[234:237], v[186:189], v[36:39]
	v_mfma_f32_16x16x32_bf16 v[32:35], v[242:245], v[186:189], v[32:35]
	v_mfma_f32_16x16x32_bf16 v[20:23], v[234:237], v[218:221], v[20:23]
	v_mfma_f32_16x16x32_bf16 v[16:19], v[242:245], v[218:221], v[16:19]
	v_mfma_f32_16x16x32_bf16 v[4:7], v[234:237], v[226:229], v[4:7]
	v_mfma_f32_16x16x32_bf16 v[0:3], v[242:245], v[226:229], v[0:3]
	s_setprio 0
	s_add_i32 s2, 0, 0x18000
	v_add_u32_e32 v158, s2, v147
	s_barrier
	ds_read_b128 v[142:145], v158
	ds_read_b128 v[150:153], v158 offset:1024
	ds_read_b128 v[166:169], v158 offset:2048
	ds_read_b128 v[170:173], v158 offset:3072
	s_add_u32 s12, s12, s22
	s_addc_u32 s13, s13, 0
	s_mov_b32 m0, s76
	ds_read_b128 v[174:177], v149 offset:32768
	ds_read_b128 v[178:181], v149 offset:33792
	ds_read_b128 v[182:185], v149 offset:34816
	ds_read_b128 v[186:189], v149 offset:35840
	ds_read_b128 v[214:217], v149 offset:36864
	ds_read_b128 v[218:221], v149 offset:37888
	ds_read_b128 v[222:225], v149 offset:38912
	ds_read_b128 v[226:229], v149 offset:39936
	global_load_lds_dwordx4 v128, s[12:13]
	s_mov_b32 m0, s77
	s_nop 0
	global_load_lds_dwordx4 v132, s[12:13]
	s_waitcnt lgkmcnt(8)
	s_barrier
	s_waitcnt lgkmcnt(0)
	s_setprio 1
	s_waitcnt lgkmcnt(0)
	v_mfma_f32_16x16x32_bf16 v[124:127], v[142:145], v[174:177], v[124:127]
	v_mfma_f32_16x16x32_bf16 v[120:123], v[166:169], v[174:177], v[120:123]
	v_mfma_f32_16x16x32_bf16 v[108:111], v[142:145], v[182:185], v[108:111]
	v_mfma_f32_16x16x32_bf16 v[104:107], v[166:169], v[182:185], v[104:107]
	v_mfma_f32_16x16x32_bf16 v[92:95], v[142:145], v[214:217], v[92:95]
	v_mfma_f32_16x16x32_bf16 v[88:91], v[166:169], v[214:217], v[88:91]
	v_mfma_f32_16x16x32_bf16 v[76:79], v[142:145], v[222:225], v[76:79]
	v_mfma_f32_16x16x32_bf16 v[72:75], v[166:169], v[222:225], v[72:75]
	v_mfma_f32_16x16x32_bf16 v[124:127], v[150:153], v[178:181], v[124:127]
	v_mfma_f32_16x16x32_bf16 v[120:123], v[170:173], v[178:181], v[120:123]
	v_mfma_f32_16x16x32_bf16 v[108:111], v[150:153], v[186:189], v[108:111]
	v_mfma_f32_16x16x32_bf16 v[104:107], v[170:173], v[186:189], v[104:107]
	v_mfma_f32_16x16x32_bf16 v[92:95], v[150:153], v[218:221], v[92:95]
	v_mfma_f32_16x16x32_bf16 v[88:91], v[170:173], v[218:221], v[88:91]
	v_mfma_f32_16x16x32_bf16 v[76:79], v[150:153], v[226:229], v[76:79]
	v_mfma_f32_16x16x32_bf16 v[72:75], v[170:173], v[226:229], v[72:75]
	s_setprio 0
	s_barrier
	s_add_i32 s12, 0, 0x1c000
	s_add_i32 s2, s2, s0
	v_add_u32_e32 v158, s12, v147
	v_lshl_add_u64 v[154:155], v[154:155], 0, s[70:71]
	s_mov_b32 m0, s2
	ds_read_b128 v[230:233], v158
	ds_read_b128 v[234:237], v158 offset:1024
	ds_read_b128 v[238:241], v158 offset:2048
	ds_read_b128 v[242:245], v158 offset:3072
	global_load_lds_dwordx4 v[154:155], off
	v_lshl_add_u64 v[154:155], v[190:191], 0, s[70:71]
	s_add_i32 m0, s2, 0x2000
	s_nop 0
	global_load_lds_dwordx4 v[154:155], off
	s_barrier
	s_waitcnt lgkmcnt(0)
	s_setprio 1
	s_waitcnt lgkmcnt(0)
	v_mfma_f32_16x16x32_bf16 v[116:119], v[230:233], v[174:177], v[116:119]
	v_mfma_f32_16x16x32_bf16 v[112:115], v[238:241], v[174:177], v[112:115]
	v_mfma_f32_16x16x32_bf16 v[100:103], v[230:233], v[182:185], v[100:103]
	v_mfma_f32_16x16x32_bf16 v[96:99], v[238:241], v[182:185], v[96:99]
	v_mfma_f32_16x16x32_bf16 v[84:87], v[230:233], v[214:217], v[84:87]
	v_mfma_f32_16x16x32_bf16 v[80:83], v[238:241], v[214:217], v[80:83]
	v_mfma_f32_16x16x32_bf16 v[68:71], v[230:233], v[222:225], v[68:71]
	v_mfma_f32_16x16x32_bf16 v[64:67], v[238:241], v[222:225], v[64:67]
	v_mfma_f32_16x16x32_bf16 v[116:119], v[234:237], v[178:181], v[116:119]
	v_mfma_f32_16x16x32_bf16 v[112:115], v[242:245], v[178:181], v[112:115]
	v_mfma_f32_16x16x32_bf16 v[100:103], v[234:237], v[186:189], v[100:103]
	v_mfma_f32_16x16x32_bf16 v[96:99], v[242:245], v[186:189], v[96:99]
	v_mfma_f32_16x16x32_bf16 v[84:87], v[234:237], v[218:221], v[84:87]
	v_mfma_f32_16x16x32_bf16 v[80:83], v[242:245], v[218:221], v[80:83]
	v_mfma_f32_16x16x32_bf16 v[68:71], v[234:237], v[226:229], v[68:71]
	v_mfma_f32_16x16x32_bf16 v[64:67], v[242:245], v[226:229], v[64:67]
	s_setprio 0
	s_mov_b32 m0, s79
	v_lshl_add_u64 v[154:155], v[202:203], 0, s[70:71]
	s_barrier
	ds_read_b128 v[174:177], v149 offset:49152
	ds_read_b128 v[178:181], v149 offset:50176
	ds_read_b128 v[182:185], v149 offset:51200
	ds_read_b128 v[186:189], v149 offset:52224
	ds_read_b128 v[214:217], v149 offset:53248
	ds_read_b128 v[218:221], v149 offset:54272
	ds_read_b128 v[222:225], v149 offset:55296
	ds_read_b128 v[226:229], v149 offset:56320
	global_load_lds_dwordx4 v[154:155], off
	v_lshl_add_u64 v[154:155], v[204:205], 0, s[70:71]
	s_mov_b32 m0, s80
	s_nop 0
	global_load_lds_dwordx4 v[154:155], off
	s_barrier
	s_waitcnt lgkmcnt(0)
	s_setprio 1
	s_waitcnt lgkmcnt(0)
	v_mfma_f32_16x16x32_bf16 v[60:63], v[142:145], v[174:177], v[60:63]
	v_mfma_f32_16x16x32_bf16 v[56:59], v[166:169], v[174:177], v[56:59]
	v_mfma_f32_16x16x32_bf16 v[44:47], v[142:145], v[182:185], v[44:47]
	v_mfma_f32_16x16x32_bf16 v[40:43], v[166:169], v[182:185], v[40:43]
	v_mfma_f32_16x16x32_bf16 v[28:31], v[142:145], v[214:217], v[28:31]
	v_mfma_f32_16x16x32_bf16 v[24:27], v[166:169], v[214:217], v[24:27]
	v_mfma_f32_16x16x32_bf16 v[12:15], v[142:145], v[222:225], v[12:15]
	v_mfma_f32_16x16x32_bf16 v[8:11], v[166:169], v[222:225], v[8:11]
	v_mfma_f32_16x16x32_bf16 v[60:63], v[150:153], v[178:181], v[60:63]
	v_mfma_f32_16x16x32_bf16 v[56:59], v[170:173], v[178:181], v[56:59]
	v_mfma_f32_16x16x32_bf16 v[44:47], v[150:153], v[186:189], v[44:47]
	v_mfma_f32_16x16x32_bf16 v[40:43], v[170:173], v[186:189], v[40:43]
	v_mfma_f32_16x16x32_bf16 v[28:31], v[150:153], v[218:221], v[28:31]
	v_mfma_f32_16x16x32_bf16 v[24:27], v[170:173], v[218:221], v[24:27]
	v_mfma_f32_16x16x32_bf16 v[12:15], v[150:153], v[226:229], v[12:15]
	v_mfma_f32_16x16x32_bf16 v[8:11], v[170:173], v[226:229], v[8:11]
	s_setprio 0
	s_barrier
	s_add_i32 s2, s12, s0
	v_lshl_add_u64 v[142:143], v[246:247], 0, s[70:71]
	s_mov_b32 m0, s2
	s_nop 0
	global_load_lds_dwordx4 v[142:143], off
	v_lshl_add_u64 v[142:143], v[248:249], 0, s[70:71]
	s_add_i32 m0, s2, 0x2000
	s_nop 0
	global_load_lds_dwordx4 v[142:143], off
	s_waitcnt vmcnt(6)
	s_barrier
	s_setprio 1
	v_mfma_f32_16x16x32_bf16 v[52:55], v[230:233], v[174:177], v[52:55]
	v_mfma_f32_16x16x32_bf16 v[48:51], v[238:241], v[174:177], v[48:51]
	v_mfma_f32_16x16x32_bf16 v[36:39], v[230:233], v[182:185], v[36:39]
	v_mfma_f32_16x16x32_bf16 v[32:35], v[238:241], v[182:185], v[32:35]
	v_mfma_f32_16x16x32_bf16 v[20:23], v[230:233], v[214:217], v[20:23]
	v_mfma_f32_16x16x32_bf16 v[16:19], v[238:241], v[214:217], v[16:19]
	v_mfma_f32_16x16x32_bf16 v[4:7], v[230:233], v[222:225], v[4:7]
	v_mfma_f32_16x16x32_bf16 v[0:3], v[238:241], v[222:225], v[0:3]
	v_mfma_f32_16x16x32_bf16 v[52:55], v[234:237], v[178:181], v[52:55]
	v_mfma_f32_16x16x32_bf16 v[48:51], v[242:245], v[178:181], v[48:51]
	v_mfma_f32_16x16x32_bf16 v[36:39], v[234:237], v[186:189], v[36:39]
	v_mfma_f32_16x16x32_bf16 v[32:35], v[242:245], v[186:189], v[32:35]
	v_mfma_f32_16x16x32_bf16 v[20:23], v[234:237], v[218:221], v[20:23]
	v_mfma_f32_16x16x32_bf16 v[16:19], v[242:245], v[218:221], v[16:19]
	v_mfma_f32_16x16x32_bf16 v[4:7], v[234:237], v[226:229], v[4:7]
	v_mfma_f32_16x16x32_bf16 v[0:3], v[242:245], v[226:229], v[0:3]
	s_setprio 0
	s_add_u32 s10, s10, 0x100
	s_addc_u32 s11, s11, 0
	s_add_u32 s73, s73, 0x100
	s_addc_u32 vcc_lo, vcc_lo, 0
	s_cmp_ge_u32 vcc_hi, s78
	s_mov_b32 s12, vcc_hi
	s_barrier
	s_cbranch_scc0 .LBB0_605
	v_lshl_add_u32 v142, s72, 8, v146
	v_ashrrev_i32_e32 v143, 31, v142
	v_lshl_or_b32 v158, s48, 8, v148
	v_lshlrev_b64 v[144:145], 10, v[142:143]
	v_lshl_add_u64 v[144:145], v[144:145], 0, v[158:159]
	v_cndmask_b32_e64 v145, 0, 1, s[58:59]
	v_pk_mul_f32 v[126:127], s[18:19], v[126:127]
	v_pk_mul_f32 v[124:125], s[16:17], v[124:125]
	v_cmp_ne_u32_e64 s[10:11], 1, v145
	s_andn2_b64 vcc, exec, s[58:59]
	s_mov_b64 s[12:13], -1
	s_cbranch_vccnz .LBB0_608
	v_lshlrev_b32_e32 v145, 2, v144
	s_mov_b64 s[12:13], 0
	buffer_store_dwordx4 v[124:127], v145, s[28:31], 0 offen sc1

.LBB0_791:
	v_mov_b64_e32 v[0:1], 0x580
	s_ashr_i32 s21, s20, 31
	v_cmp_lt_i64_e32 vcc, s[22:23], v[0:1]
	s_lshl_b64 s[22:23], s[20:21], 19
	s_add_u32 s22, s96, s22
	s_addc_u32 s23, s97, s23
	s_and_b64 s[24:25], vcc, exec
	s_cselect_b32 s9, s23, s59
	s_cselect_b32 s21, s22, s58
	s_ashr_i32 s19, s18, 31
	s_lshl_b64 s[24:25], s[18:19], 19
	s_add_u32 s24, s35, s24
	s_addc_u32 s25, s47, s25
	s_and_b64 s[66:67], vcc, exec
	s_cselect_b32 s19, s25, s63
	s_cselect_b32 s29, s24, s62
	s_add_u32 s58, s58, 0x40080
	s_addc_u32 s59, s59, 0
	s_add_u32 s43, s62, 0x100
	s_addc_u32 s51, s63, 0
	s_mov_b32 s75, -2
	s_add_u32 s62, s58, 0xfffc0080
	s_addc_u32 s63, s59, -1
	s_add_i32 s76, 0, 0x10000
	v_add_u32_e32 v138, s76, v142
	ds_read_b128 v[146:149], v138
	ds_read_b128 v[150:153], v138 offset:1024
	ds_read_b128 v[166:169], v138 offset:2048
	ds_read_b128 v[170:173], v138 offset:3072
	s_cmp_eq_u32 s75, 12
	s_cselect_b32 s67, s9, s63
	s_cselect_b32 s66, s21, s62
	s_cselect_b32 s63, s19, s51
	s_cselect_b32 s62, s29, s43
	s_add_i32 m0, s48, 0xc000
	ds_read_b128 v[174:177], v145
	ds_read_b128 v[178:181], v145 offset:1024
	ds_read_b128 v[182:185], v145 offset:2048
	ds_read_b128 v[186:189], v145 offset:3072
	ds_read_b128 v[214:217], v145 offset:4096
	ds_read_b128 v[218:221], v145 offset:5120
	ds_read_b128 v[222:225], v145 offset:6144
	ds_read_b128 v[226:229], v145 offset:7168
	global_load_lds_dwordx4 v134, s[58:59]
	s_add_i32 m0, s48, 0xe000
	s_nop 0
	global_load_lds_dwordx4 v136, s[58:59]
	s_waitcnt lgkmcnt(8)
	s_barrier
	s_waitcnt lgkmcnt(0)
	s_setprio 1
	s_waitcnt lgkmcnt(0)
	v_mfma_f32_16x16x32_bf16 v[124:127], v[146:149], v[174:177], 0
	v_mfma_f32_16x16x32_bf16 v[116:119], v[166:169], v[174:177], 0
	v_mfma_f32_16x16x32_bf16 v[108:111], v[146:149], v[182:185], 0
	v_mfma_f32_16x16x32_bf16 v[100:103], v[166:169], v[182:185], 0
	v_mfma_f32_16x16x32_bf16 v[92:95], v[146:149], v[214:217], 0
	v_mfma_f32_16x16x32_bf16 v[84:87], v[166:169], v[214:217], 0
	v_mfma_f32_16x16x32_bf16 v[76:79], v[146:149], v[222:225], 0
	v_mfma_f32_16x16x32_bf16 v[68:71], v[166:169], v[222:225], 0
	v_mfma_f32_16x16x32_bf16 v[124:127], v[150:153], v[178:181], v[124:127]
	v_mfma_f32_16x16x32_bf16 v[116:119], v[170:173], v[178:181], v[116:119]
	v_mfma_f32_16x16x32_bf16 v[108:111], v[150:153], v[186:189], v[108:111]
	v_mfma_f32_16x16x32_bf16 v[100:103], v[170:173], v[186:189], v[100:103]
	v_mfma_f32_16x16x32_bf16 v[92:95], v[150:153], v[218:221], v[92:95]
	v_mfma_f32_16x16x32_bf16 v[84:87], v[170:173], v[218:221], v[84:87]
	v_mfma_f32_16x16x32_bf16 v[76:79], v[150:153], v[226:229], v[76:79]
	v_mfma_f32_16x16x32_bf16 v[68:71], v[170:173], v[226:229], v[68:71]
	s_setprio 0
	s_barrier
	s_add_i32 s78, 0, 0x14000
	v_add_u32_e32 v138, s78, v142
	s_add_i32 s76, s76, s31
	ds_read_b128 v[230:233], v138
	ds_read_b128 v[234:237], v138 offset:1024
	ds_read_b128 v[238:241], v138 offset:2048
	ds_read_b128 v[242:245], v138 offset:3072
	v_lshl_add_u64 v[138:139], s[62:63], 0, v[158:159]
	s_mov_b32 m0, s76
	v_lshl_add_u64 v[154:155], s[62:63], 0, v[132:133]
	global_load_lds_dwordx4 v158, s[62:63]
	s_add_i32 m0, s76, 0x2000
	s_nop 0
	global_load_lds_dwordx4 v132, s[62:63]
	s_barrier
	s_waitcnt lgkmcnt(0)
	s_setprio 1
	s_waitcnt lgkmcnt(0)
	v_mfma_f32_16x16x32_bf16 v[120:123], v[230:233], v[174:177], 0
	v_mfma_f32_16x16x32_bf16 v[112:115], v[238:241], v[174:177], 0
	v_mfma_f32_16x16x32_bf16 v[104:107], v[230:233], v[182:185], 0
	v_mfma_f32_16x16x32_bf16 v[96:99], v[238:241], v[182:185], 0
	v_mfma_f32_16x16x32_bf16 v[88:91], v[230:233], v[214:217], 0
	v_mfma_f32_16x16x32_bf16 v[80:83], v[238:241], v[214:217], 0
	v_mfma_f32_16x16x32_bf16 v[72:75], v[230:233], v[222:225], 0
	v_mfma_f32_16x16x32_bf16 v[64:67], v[238:241], v[222:225], 0
	v_mfma_f32_16x16x32_bf16 v[120:123], v[234:237], v[178:181], v[120:123]
	v_mfma_f32_16x16x32_bf16 v[112:115], v[242:245], v[178:181], v[112:115]
	v_mfma_f32_16x16x32_bf16 v[104:107], v[234:237], v[186:189], v[104:107]
	v_mfma_f32_16x16x32_bf16 v[96:99], v[242:245], v[186:189], v[96:99]
	v_mfma_f32_16x16x32_bf16 v[88:91], v[234:237], v[218:221], v[88:91]
	v_mfma_f32_16x16x32_bf16 v[80:83], v[242:245], v[218:221], v[80:83]
	v_mfma_f32_16x16x32_bf16 v[72:75], v[234:237], v[226:229], v[72:75]
	v_mfma_f32_16x16x32_bf16 v[64:67], v[242:245], v[226:229], v[64:67]
	s_setprio 0
	s_mov_b32 m0, s48
	v_lshl_add_u64 v[190:191], s[66:67], 0, v[128:129]
	s_barrier
	ds_read_b128 v[174:177], v145 offset:16384
	ds_read_b128 v[178:181], v145 offset:17408
	ds_read_b128 v[182:185], v145 offset:18432
	ds_read_b128 v[186:189], v145 offset:19456
	ds_read_b128 v[214:217], v145 offset:20480
	ds_read_b128 v[218:221], v145 offset:21504
	ds_read_b128 v[222:225], v145 offset:22528
	ds_read_b128 v[226:229], v145 offset:23552
	global_load_lds_dwordx4 v128, s[66:67]
	v_lshl_add_u64 v[202:203], s[66:67], 0, v[130:131]
	s_mov_b32 m0, s50
	s_nop 0
	global_load_lds_dwordx4 v130, s[66:67]
	s_barrier
	s_waitcnt lgkmcnt(0)
	s_setprio 1
	s_waitcnt lgkmcnt(0)
	v_mfma_f32_16x16x32_bf16 v[60:63], v[146:149], v[174:177], 0
	v_mfma_f32_16x16x32_bf16 v[52:55], v[166:169], v[174:177], 0
	v_mfma_f32_16x16x32_bf16 v[44:47], v[146:149], v[182:185], 0
	v_mfma_f32_16x16x32_bf16 v[36:39], v[166:169], v[182:185], 0
	v_mfma_f32_16x16x32_bf16 v[28:31], v[146:149], v[214:217], 0
	v_mfma_f32_16x16x32_bf16 v[20:23], v[166:169], v[214:217], 0
	v_mfma_f32_16x16x32_bf16 v[12:15], v[146:149], v[222:225], 0
	v_mfma_f32_16x16x32_bf16 v[4:7], v[166:169], v[222:225], 0
	v_mfma_f32_16x16x32_bf16 v[60:63], v[150:153], v[178:181], v[60:63]
	v_mfma_f32_16x16x32_bf16 v[52:55], v[170:173], v[178:181], v[52:55]
	v_mfma_f32_16x16x32_bf16 v[44:47], v[150:153], v[186:189], v[44:47]
	v_mfma_f32_16x16x32_bf16 v[36:39], v[170:173], v[186:189], v[36:39]
	v_mfma_f32_16x16x32_bf16 v[28:31], v[150:153], v[218:221], v[28:31]
	v_mfma_f32_16x16x32_bf16 v[20:23], v[170:173], v[218:221], v[20:23]
	v_mfma_f32_16x16x32_bf16 v[12:15], v[150:153], v[226:229], v[12:15]
	v_mfma_f32_16x16x32_bf16 v[4:7], v[170:173], v[226:229], v[4:7]
	s_setprio 0
	s_barrier
	s_add_u32 s76, s62, 0x40000
	s_addc_u32 s77, s63, 0
	s_add_i32 s78, s78, s31
	s_mov_b32 m0, s78
	s_nop 0
	global_load_lds_dwordx4 v158, s[76:77]
	s_add_i32 m0, s78, 0x2000
	s_nop 0
	global_load_lds_dwordx4 v132, s[76:77]
	s_waitcnt vmcnt(6)
	s_barrier
	s_setprio 1
	v_mfma_f32_16x16x32_bf16 v[56:59], v[230:233], v[174:177], 0
	v_mfma_f32_16x16x32_bf16 v[48:51], v[238:241], v[174:177], 0
	v_mfma_f32_16x16x32_bf16 v[40:43], v[230:233], v[182:185], 0
	v_mfma_f32_16x16x32_bf16 v[32:35], v[238:241], v[182:185], 0
	v_mfma_f32_16x16x32_bf16 v[24:27], v[230:233], v[214:217], 0
	v_mfma_f32_16x16x32_bf16 v[16:19], v[238:241], v[214:217], 0
	v_mfma_f32_16x16x32_bf16 v[8:11], v[230:233], v[222:225], 0
	v_mfma_f32_16x16x32_bf16 v[0:3], v[238:241], v[222:225], 0
	v_mfma_f32_16x16x32_bf16 v[56:59], v[234:237], v[178:181], v[56:59]
	v_mfma_f32_16x16x32_bf16 v[48:51], v[242:245], v[178:181], v[48:51]
	v_mfma_f32_16x16x32_bf16 v[40:43], v[234:237], v[186:189], v[40:43]
	v_mfma_f32_16x16x32_bf16 v[32:35], v[242:245], v[186:189], v[32:35]
	v_mfma_f32_16x16x32_bf16 v[24:27], v[234:237], v[218:221], v[24:27]
	v_mfma_f32_16x16x32_bf16 v[16:19], v[242:245], v[218:221], v[16:19]
	v_mfma_f32_16x16x32_bf16 v[8:11], v[234:237], v[226:229], v[8:11]
	v_mfma_f32_16x16x32_bf16 v[0:3], v[242:245], v[226:229], v[0:3]
	s_setprio 0
	s_add_i32 s76, 0, 0x18000
	v_add_u32_e32 v140, s76, v142
	s_barrier
	ds_read_b128 v[146:149], v140
	ds_read_b128 v[150:153], v140 offset:1024
	ds_read_b128 v[166:169], v140 offset:2048
	ds_read_b128 v[170:173], v140 offset:3072
	s_add_u32 s66, s66, 0x40000
	s_addc_u32 s67, s67, 0
	s_mov_b32 m0, s65
	ds_read_b128 v[174:177], v145 offset:32768
	ds_read_b128 v[178:181], v145 offset:33792
	ds_read_b128 v[182:185], v145 offset:34816
	ds_read_b128 v[186:189], v145 offset:35840
	ds_read_b128 v[214:217], v145 offset:36864
	ds_read_b128 v[218:221], v145 offset:37888
	ds_read_b128 v[222:225], v145 offset:38912
	ds_read_b128 v[226:229], v145 offset:39936
	global_load_lds_dwordx4 v128, s[66:67]
	s_mov_b32 m0, s68
	s_nop 0
	global_load_lds_dwordx4 v130, s[66:67]
	s_waitcnt lgkmcnt(8)
	s_barrier
	s_waitcnt lgkmcnt(0)
	s_setprio 1
	s_waitcnt lgkmcnt(0)
	v_mfma_f32_16x16x32_bf16 v[124:127], v[146:149], v[174:177], v[124:127]
	v_mfma_f32_16x16x32_bf16 v[116:119], v[166:169], v[174:177], v[116:119]
	v_mfma_f32_16x16x32_bf16 v[108:111], v[146:149], v[182:185], v[108:111]
	v_mfma_f32_16x16x32_bf16 v[100:103], v[166:169], v[182:185], v[100:103]
	v_mfma_f32_16x16x32_bf16 v[92:95], v[146:149], v[214:217], v[92:95]
	v_mfma_f32_16x16x32_bf16 v[84:87], v[166:169], v[214:217], v[84:87]
	v_mfma_f32_16x16x32_bf16 v[76:79], v[146:149], v[222:225], v[76:79]
	v_mfma_f32_16x16x32_bf16 v[68:71], v[166:169], v[222:225], v[68:71]
	v_mfma_f32_16x16x32_bf16 v[124:127], v[150:153], v[178:181], v[124:127]
	v_mfma_f32_16x16x32_bf16 v[116:119], v[170:173], v[178:181], v[116:119]
	v_mfma_f32_16x16x32_bf16 v[108:111], v[150:153], v[186:189], v[108:111]
	v_mfma_f32_16x16x32_bf16 v[100:103], v[170:173], v[186:189], v[100:103]
	v_mfma_f32_16x16x32_bf16 v[92:95], v[150:153], v[218:221], v[92:95]
	v_mfma_f32_16x16x32_bf16 v[84:87], v[170:173], v[218:221], v[84:87]
	v_mfma_f32_16x16x32_bf16 v[76:79], v[150:153], v[226:229], v[76:79]
	v_mfma_f32_16x16x32_bf16 v[68:71], v[170:173], v[226:229], v[68:71]
	s_setprio 0
	s_barrier
	s_add_i32 s66, 0, 0x1c000
	s_add_i32 s67, s76, s31
	v_add_u32_e32 v140, s66, v142
	v_lshl_add_u64 v[138:139], v[138:139], 0, s[70:71]
	s_mov_b32 m0, s67
	ds_read_b128 v[230:233], v140
	ds_read_b128 v[234:237], v140 offset:1024
	ds_read_b128 v[238:241], v140 offset:2048
	ds_read_b128 v[242:245], v140 offset:3072
	global_load_lds_dwordx4 v[138:139], off
	v_lshl_add_u64 v[138:139], v[154:155], 0, s[70:71]
	s_add_i32 m0, s67, 0x2000
	s_nop 0
	global_load_lds_dwordx4 v[138:139], off
	s_barrier
	s_waitcnt lgkmcnt(0)
	s_setprio 1
	s_waitcnt lgkmcnt(0)
	v_mfma_f32_16x16x32_bf16 v[120:123], v[230:233], v[174:177], v[120:123]
	v_mfma_f32_16x16x32_bf16 v[112:115], v[238:241], v[174:177], v[112:115]
	v_mfma_f32_16x16x32_bf16 v[104:107], v[230:233], v[182:185], v[104:107]
	v_mfma_f32_16x16x32_bf16 v[96:99], v[238:241], v[182:185], v[96:99]
	v_mfma_f32_16x16x32_bf16 v[88:91], v[230:233], v[214:217], v[88:91]
	v_mfma_f32_16x16x32_bf16 v[80:83], v[238:241], v[214:217], v[80:83]
	v_mfma_f32_16x16x32_bf16 v[72:75], v[230:233], v[222:225], v[72:75]
	v_mfma_f32_16x16x32_bf16 v[64:67], v[238:241], v[222:225], v[64:67]
	v_mfma_f32_16x16x32_bf16 v[120:123], v[234:237], v[178:181], v[120:123]
	v_mfma_f32_16x16x32_bf16 v[112:115], v[242:245], v[178:181], v[112:115]
	v_mfma_f32_16x16x32_bf16 v[104:107], v[234:237], v[186:189], v[104:107]
	v_mfma_f32_16x16x32_bf16 v[96:99], v[242:245], v[186:189], v[96:99]
	v_mfma_f32_16x16x32_bf16 v[88:91], v[234:237], v[218:221], v[88:91]
	v_mfma_f32_16x16x32_bf16 v[80:83], v[242:245], v[218:221], v[80:83]
	v_mfma_f32_16x16x32_bf16 v[72:75], v[234:237], v[226:229], v[72:75]
	v_mfma_f32_16x16x32_bf16 v[64:67], v[242:245], v[226:229], v[64:67]
	s_setprio 0
	s_mov_b32 m0, s69
	v_lshl_add_u64 v[138:139], v[190:191], 0, s[70:71]
	s_barrier
	ds_read_b128 v[174:177], v145 offset:49152
	ds_read_b128 v[178:181], v145 offset:50176
	ds_read_b128 v[182:185], v145 offset:51200
	ds_read_b128 v[186:189], v145 offset:52224
	ds_read_b128 v[214:217], v145 offset:53248
	ds_read_b128 v[218:221], v145 offset:54272
	ds_read_b128 v[222:225], v145 offset:55296
	ds_read_b128 v[226:229], v145 offset:56320
	global_load_lds_dwordx4 v[138:139], off
	v_lshl_add_u64 v[138:139], v[202:203], 0, s[70:71]
	s_mov_b32 m0, s72
	s_nop 0
	global_load_lds_dwordx4 v[138:139], off
	s_barrier
	s_waitcnt lgkmcnt(0)
	s_setprio 1
	s_waitcnt lgkmcnt(0)
	v_mfma_f32_16x16x32_bf16 v[60:63], v[146:149], v[174:177], v[60:63]
	v_mfma_f32_16x16x32_bf16 v[52:55], v[166:169], v[174:177], v[52:55]
	v_mfma_f32_16x16x32_bf16 v[44:47], v[146:149], v[182:185], v[44:47]
	v_mfma_f32_16x16x32_bf16 v[36:39], v[166:169], v[182:185], v[36:39]
	v_mfma_f32_16x16x32_bf16 v[28:31], v[146:149], v[214:217], v[28:31]
	v_mfma_f32_16x16x32_bf16 v[20:23], v[166:169], v[214:217], v[20:23]
	v_mfma_f32_16x16x32_bf16 v[12:15], v[146:149], v[222:225], v[12:15]
	v_mfma_f32_16x16x32_bf16 v[4:7], v[166:169], v[222:225], v[4:7]
	v_mfma_f32_16x16x32_bf16 v[60:63], v[150:153], v[178:181], v[60:63]
	v_mfma_f32_16x16x32_bf16 v[52:55], v[170:173], v[178:181], v[52:55]
	v_mfma_f32_16x16x32_bf16 v[44:47], v[150:153], v[186:189], v[44:47]
	v_mfma_f32_16x16x32_bf16 v[36:39], v[170:173], v[186:189], v[36:39]
	v_mfma_f32_16x16x32_bf16 v[28:31], v[150:153], v[218:221], v[28:31]
	v_mfma_f32_16x16x32_bf16 v[20:23], v[170:173], v[218:221], v[20:23]
	v_mfma_f32_16x16x32_bf16 v[12:15], v[150:153], v[226:229], v[12:15]
	v_mfma_f32_16x16x32_bf16 v[4:7], v[170:173], v[226:229], v[4:7]
	s_setprio 0
	s_barrier
	s_add_u32 s62, s62, 0x40080
	s_addc_u32 s63, s63, 0
	s_add_i32 s66, s66, s31
	s_mov_b32 m0, s66
	s_nop 0
	global_load_lds_dwordx4 v158, s[62:63]
	s_add_i32 m0, s66, 0x2000
	s_nop 0
	global_load_lds_dwordx4 v132, s[62:63]
	s_waitcnt vmcnt(6)
	s_barrier
	s_setprio 1
	v_mfma_f32_16x16x32_bf16 v[56:59], v[230:233], v[174:177], v[56:59]
	v_mfma_f32_16x16x32_bf16 v[48:51], v[238:241], v[174:177], v[48:51]
	v_mfma_f32_16x16x32_bf16 v[40:43], v[230:233], v[182:185], v[40:43]
	v_mfma_f32_16x16x32_bf16 v[32:35], v[238:241], v[182:185], v[32:35]
	v_mfma_f32_16x16x32_bf16 v[24:27], v[230:233], v[214:217], v[24:27]
	v_mfma_f32_16x16x32_bf16 v[16:19], v[238:241], v[214:217], v[16:19]
	v_mfma_f32_16x16x32_bf16 v[8:11], v[230:233], v[222:225], v[8:11]
	v_mfma_f32_16x16x32_bf16 v[0:3], v[238:241], v[222:225], v[0:3]
	v_mfma_f32_16x16x32_bf16 v[56:59], v[234:237], v[178:181], v[56:59]
	v_mfma_f32_16x16x32_bf16 v[48:51], v[242:245], v[178:181], v[48:51]
	v_mfma_f32_16x16x32_bf16 v[40:43], v[234:237], v[186:189], v[40:43]
	v_mfma_f32_16x16x32_bf16 v[32:35], v[242:245], v[186:189], v[32:35]
	v_mfma_f32_16x16x32_bf16 v[24:27], v[234:237], v[218:221], v[24:27]
	v_mfma_f32_16x16x32_bf16 v[16:19], v[242:245], v[218:221], v[16:19]
	v_mfma_f32_16x16x32_bf16 v[8:11], v[234:237], v[226:229], v[8:11]
	v_mfma_f32_16x16x32_bf16 v[0:3], v[242:245], v[226:229], v[0:3]
	s_setprio 0
	s_add_i32 s75, s75, 2
	s_add_u32 s58, s58, 0x100
	s_addc_u32 s59, s59, 0
	s_add_u32 s43, s43, 0x100
	s_addc_u32 s51, s51, 0
	s_cmp_gt_u32 s75, 13
	s_barrier
	s_cbranch_scc1 .Lzp_exit3
.LBB0_792:
	s_add_u32 s62, s58, 0xfffc0080
	s_addc_u32 s63, s59, -1
	s_add_i32 s76, 0, 0x10000
	v_add_u32_e32 v138, s76, v142
	ds_read_b128 v[146:149], v138
	ds_read_b128 v[150:153], v138 offset:1024
	ds_read_b128 v[166:169], v138 offset:2048
	ds_read_b128 v[170:173], v138 offset:3072
	s_cmp_eq_u32 s75, 12
	s_cselect_b32 s67, s9, s63
	s_cselect_b32 s66, s21, s62
	s_cselect_b32 s63, s19, s51
	s_cselect_b32 s62, s29, s43
	s_add_i32 m0, s48, 0xc000
	ds_read_b128 v[174:177], v145
	ds_read_b128 v[178:181], v145 offset:1024
	ds_read_b128 v[182:185], v145 offset:2048
	ds_read_b128 v[186:189], v145 offset:3072
	ds_read_b128 v[214:217], v145 offset:4096
	ds_read_b128 v[218:221], v145 offset:5120
	ds_read_b128 v[222:225], v145 offset:6144
	ds_read_b128 v[226:229], v145 offset:7168
	global_load_lds_dwordx4 v134, s[58:59]
	s_add_i32 m0, s48, 0xe000
	s_nop 0
	global_load_lds_dwordx4 v136, s[58:59]
	s_waitcnt lgkmcnt(8)
	s_barrier
	s_waitcnt lgkmcnt(0)
	s_setprio 1
	s_waitcnt lgkmcnt(0)
	v_mfma_f32_16x16x32_bf16 v[124:127], v[146:149], v[174:177], v[124:127]
	v_mfma_f32_16x16x32_bf16 v[116:119], v[166:169], v[174:177], v[116:119]
	v_mfma_f32_16x16x32_bf16 v[108:111], v[146:149], v[182:185], v[108:111]
	v_mfma_f32_16x16x32_bf16 v[100:103], v[166:169], v[182:185], v[100:103]
	v_mfma_f32_16x16x32_bf16 v[92:95], v[146:149], v[214:217], v[92:95]
	v_mfma_f32_16x16x32_bf16 v[84:87], v[166:169], v[214:217], v[84:87]
	v_mfma_f32_16x16x32_bf16 v[76:79], v[146:149], v[222:225], v[76:79]
	v_mfma_f32_16x16x32_bf16 v[68:71], v[166:169], v[222:225], v[68:71]
	v_mfma_f32_16x16x32_bf16 v[124:127], v[150:153], v[178:181], v[124:127]
	v_mfma_f32_16x16x32_bf16 v[116:119], v[170:173], v[178:181], v[116:119]
	v_mfma_f32_16x16x32_bf16 v[108:111], v[150:153], v[186:189], v[108:111]
	v_mfma_f32_16x16x32_bf16 v[100:103], v[170:173], v[186:189], v[100:103]
	v_mfma_f32_16x16x32_bf16 v[92:95], v[150:153], v[218:221], v[92:95]
	v_mfma_f32_16x16x32_bf16 v[84:87], v[170:173], v[218:221], v[84:87]
	v_mfma_f32_16x16x32_bf16 v[76:79], v[150:153], v[226:229], v[76:79]
	v_mfma_f32_16x16x32_bf16 v[68:71], v[170:173], v[226:229], v[68:71]
	s_setprio 0
	s_barrier
	s_add_i32 s78, 0, 0x14000
	v_add_u32_e32 v138, s78, v142
	s_add_i32 s76, s76, s31
	ds_read_b128 v[230:233], v138
	ds_read_b128 v[234:237], v138 offset:1024
	ds_read_b128 v[238:241], v138 offset:2048
	ds_read_b128 v[242:245], v138 offset:3072
	v_lshl_add_u64 v[138:139], s[62:63], 0, v[158:159]
	s_mov_b32 m0, s76
	v_lshl_add_u64 v[154:155], s[62:63], 0, v[132:133]
	global_load_lds_dwordx4 v158, s[62:63]
	s_add_i32 m0, s76, 0x2000
	s_nop 0
	global_load_lds_dwordx4 v132, s[62:63]
	s_barrier
	s_waitcnt lgkmcnt(0)
	s_setprio 1
	s_waitcnt lgkmcnt(0)
	v_mfma_f32_16x16x32_bf16 v[120:123], v[230:233], v[174:177], v[120:123]
	v_mfma_f32_16x16x32_bf16 v[112:115], v[238:241], v[174:177], v[112:115]
	v_mfma_f32_16x16x32_bf16 v[104:107], v[230:233], v[182:185], v[104:107]
	v_mfma_f32_16x16x32_bf16 v[96:99], v[238:241], v[182:185], v[96:99]
	v_mfma_f32_16x16x32_bf16 v[88:91], v[230:233], v[214:217], v[88:91]
	v_mfma_f32_16x16x32_bf16 v[80:83], v[238:241], v[214:217], v[80:83]
	v_mfma_f32_16x16x32_bf16 v[72:75], v[230:233], v[222:225], v[72:75]
	v_mfma_f32_16x16x32_bf16 v[64:67], v[238:241], v[222:225], v[64:67]
	v_mfma_f32_16x16x32_bf16 v[120:123], v[234:237], v[178:181], v[120:123]
	v_mfma_f32_16x16x32_bf16 v[112:115], v[242:245], v[178:181], v[112:115]
	v_mfma_f32_16x16x32_bf16 v[104:107], v[234:237], v[186:189], v[104:107]
	v_mfma_f32_16x16x32_bf16 v[96:99], v[242:245], v[186:189], v[96:99]
	v_mfma_f32_16x16x32_bf16 v[88:91], v[234:237], v[218:221], v[88:91]
	v_mfma_f32_16x16x32_bf16 v[80:83], v[242:245], v[218:221], v[80:83]
	v_mfma_f32_16x16x32_bf16 v[72:75], v[234:237], v[226:229], v[72:75]
	v_mfma_f32_16x16x32_bf16 v[64:67], v[242:245], v[226:229], v[64:67]
	s_setprio 0
	s_mov_b32 m0, s48
	v_lshl_add_u64 v[190:191], s[66:67], 0, v[128:129]
	s_barrier
	ds_read_b128 v[174:177], v145 offset:16384
	ds_read_b128 v[178:181], v145 offset:17408
	ds_read_b128 v[182:185], v145 offset:18432
	ds_read_b128 v[186:189], v145 offset:19456
	ds_read_b128 v[214:217], v145 offset:20480
	ds_read_b128 v[218:221], v145 offset:21504
	ds_read_b128 v[222:225], v145 offset:22528
	ds_read_b128 v[226:229], v145 offset:23552
	global_load_lds_dwordx4 v128, s[66:67]
	v_lshl_add_u64 v[202:203], s[66:67], 0, v[130:131]
	s_mov_b32 m0, s50
	s_nop 0
	global_load_lds_dwordx4 v130, s[66:67]
	s_barrier
	s_waitcnt lgkmcnt(0)
	s_setprio 1
	s_waitcnt lgkmcnt(0)
	v_mfma_f32_16x16x32_bf16 v[60:63], v[146:149], v[174:177], v[60:63]
	v_mfma_f32_16x16x32_bf16 v[52:55], v[166:169], v[174:177], v[52:55]
	v_mfma_f32_16x16x32_bf16 v[44:47], v[146:149], v[182:185], v[44:47]
	v_mfma_f32_16x16x32_bf16 v[36:39], v[166:169], v[182:185], v[36:39]
	v_mfma_f32_16x16x32_bf16 v[28:31], v[146:149], v[214:217], v[28:31]
	v_mfma_f32_16x16x32_bf16 v[20:23], v[166:169], v[214:217], v[20:23]
	v_mfma_f32_16x16x32_bf16 v[12:15], v[146:149], v[222:225], v[12:15]
	v_mfma_f32_16x16x32_bf16 v[4:7], v[166:169], v[222:225], v[4:7]
	v_mfma_f32_16x16x32_bf16 v[60:63], v[150:153], v[178:181], v[60:63]
	v_mfma_f32_16x16x32_bf16 v[52:55], v[170:173], v[178:181], v[52:55]
	v_mfma_f32_16x16x32_bf16 v[44:47], v[150:153], v[186:189], v[44:47]
	v_mfma_f32_16x16x32_bf16 v[36:39], v[170:173], v[186:189], v[36:39]
	v_mfma_f32_16x16x32_bf16 v[28:31], v[150:153], v[218:221], v[28:31]
	v_mfma_f32_16x16x32_bf16 v[20:23], v[170:173], v[218:221], v[20:23]
	v_mfma_f32_16x16x32_bf16 v[12:15], v[150:153], v[226:229], v[12:15]
	v_mfma_f32_16x16x32_bf16 v[4:7], v[170:173], v[226:229], v[4:7]
	s_setprio 0
	s_barrier
	s_add_u32 s76, s62, 0x40000
	s_addc_u32 s77, s63, 0
	s_add_i32 s78, s78, s31
	s_mov_b32 m0, s78
	s_nop 0
	global_load_lds_dwordx4 v158, s[76:77]
	s_add_i32 m0, s78, 0x2000
	s_nop 0
	global_load_lds_dwordx4 v132, s[76:77]
	s_waitcnt vmcnt(6)
	s_barrier
	s_setprio 1
	v_mfma_f32_16x16x32_bf16 v[56:59], v[230:233], v[174:177], v[56:59]
	v_mfma_f32_16x16x32_bf16 v[48:51], v[238:241], v[174:177], v[48:51]
	v_mfma_f32_16x16x32_bf16 v[40:43], v[230:233], v[182:185], v[40:43]
	v_mfma_f32_16x16x32_bf16 v[32:35], v[238:241], v[182:185], v[32:35]
	v_mfma_f32_16x16x32_bf16 v[24:27], v[230:233], v[214:217], v[24:27]
	v_mfma_f32_16x16x32_bf16 v[16:19], v[238:241], v[214:217], v[16:19]
	v_mfma_f32_16x16x32_bf16 v[8:11], v[230:233], v[222:225], v[8:11]
	v_mfma_f32_16x16x32_bf16 v[0:3], v[238:241], v[222:225], v[0:3]
	v_mfma_f32_16x16x32_bf16 v[56:59], v[234:237], v[178:181], v[56:59]
	v_mfma_f32_16x16x32_bf16 v[48:51], v[242:245], v[178:181], v[48:51]
	v_mfma_f32_16x16x32_bf16 v[40:43], v[234:237], v[186:189], v[40:43]
	v_mfma_f32_16x16x32_bf16 v[32:35], v[242:245], v[186:189], v[32:35]
	v_mfma_f32_16x16x32_bf16 v[24:27], v[234:237], v[218:221], v[24:27]
	v_mfma_f32_16x16x32_bf16 v[16:19], v[242:245], v[218:221], v[16:19]
	v_mfma_f32_16x16x32_bf16 v[8:11], v[234:237], v[226:229], v[8:11]
	v_mfma_f32_16x16x32_bf16 v[0:3], v[242:245], v[226:229], v[0:3]
	s_setprio 0
	s_add_i32 s76, 0, 0x18000
	v_add_u32_e32 v140, s76, v142
	s_barrier
	ds_read_b128 v[146:149], v140
	ds_read_b128 v[150:153], v140 offset:1024
	ds_read_b128 v[166:169], v140 offset:2048
	ds_read_b128 v[170:173], v140 offset:3072
	s_add_u32 s66, s66, 0x40000
	s_addc_u32 s67, s67, 0
	s_mov_b32 m0, s65
	ds_read_b128 v[174:177], v145 offset:32768
	ds_read_b128 v[178:181], v145 offset:33792
	ds_read_b128 v[182:185], v145 offset:34816
	ds_read_b128 v[186:189], v145 offset:35840
	ds_read_b128 v[214:217], v145 offset:36864
	ds_read_b128 v[218:221], v145 offset:37888
	ds_read_b128 v[222:225], v145 offset:38912
	ds_read_b128 v[226:229], v145 offset:39936
	global_load_lds_dwordx4 v128, s[66:67]
	s_mov_b32 m0, s68
	s_nop 0
	global_load_lds_dwordx4 v130, s[66:67]
	s_waitcnt lgkmcnt(8)
	s_barrier
	s_waitcnt lgkmcnt(0)
	s_setprio 1
	s_waitcnt lgkmcnt(0)
	v_mfma_f32_16x16x32_bf16 v[124:127], v[146:149], v[174:177], v[124:127]
	v_mfma_f32_16x16x32_bf16 v[116:119], v[166:169], v[174:177], v[116:119]
	v_mfma_f32_16x16x32_bf16 v[108:111], v[146:149], v[182:185], v[108:111]
	v_mfma_f32_16x16x32_bf16 v[100:103], v[166:169], v[182:185], v[100:103]
	v_mfma_f32_16x16x32_bf16 v[92:95], v[146:149], v[214:217], v[92:95]
	v_mfma_f32_16x16x32_bf16 v[84:87], v[166:169], v[214:217], v[84:87]
	v_mfma_f32_16x16x32_bf16 v[76:79], v[146:149], v[222:225], v[76:79]
	v_mfma_f32_16x16x32_bf16 v[68:71], v[166:169], v[222:225], v[68:71]
	v_mfma_f32_16x16x32_bf16 v[124:127], v[150:153], v[178:181], v[124:127]
	v_mfma_f32_16x16x32_bf16 v[116:119], v[170:173], v[178:181], v[116:119]
	v_mfma_f32_16x16x32_bf16 v[108:111], v[150:153], v[186:189], v[108:111]
	v_mfma_f32_16x16x32_bf16 v[100:103], v[170:173], v[186:189], v[100:103]
	v_mfma_f32_16x16x32_bf16 v[92:95], v[150:153], v[218:221], v[92:95]
	v_mfma_f32_16x16x32_bf16 v[84:87], v[170:173], v[218:221], v[84:87]
	v_mfma_f32_16x16x32_bf16 v[76:79], v[150:153], v[226:229], v[76:79]
	v_mfma_f32_16x16x32_bf16 v[68:71], v[170:173], v[226:229], v[68:71]
	s_setprio 0
	s_barrier
	s_add_i32 s66, 0, 0x1c000
	s_add_i32 s67, s76, s31
	v_add_u32_e32 v140, s66, v142
	v_lshl_add_u64 v[138:139], v[138:139], 0, s[70:71]
	s_mov_b32 m0, s67
	ds_read_b128 v[230:233], v140
	ds_read_b128 v[234:237], v140 offset:1024
	ds_read_b128 v[238:241], v140 offset:2048
	ds_read_b128 v[242:245], v140 offset:3072
	global_load_lds_dwordx4 v[138:139], off
	v_lshl_add_u64 v[138:139], v[154:155], 0, s[70:71]
	s_add_i32 m0, s67, 0x2000
	s_nop 0
	global_load_lds_dwordx4 v[138:139], off
	s_barrier
	s_waitcnt lgkmcnt(0)
	s_setprio 1
	s_waitcnt lgkmcnt(0)
	v_mfma_f32_16x16x32_bf16 v[120:123], v[230:233], v[174:177], v[120:123]
	v_mfma_f32_16x16x32_bf16 v[112:115], v[238:241], v[174:177], v[112:115]
	v_mfma_f32_16x16x32_bf16 v[104:107], v[230:233], v[182:185], v[104:107]
	v_mfma_f32_16x16x32_bf16 v[96:99], v[238:241], v[182:185], v[96:99]
	v_mfma_f32_16x16x32_bf16 v[88:91], v[230:233], v[214:217], v[88:91]
	v_mfma_f32_16x16x32_bf16 v[80:83], v[238:241], v[214:217], v[80:83]
	v_mfma_f32_16x16x32_bf16 v[72:75], v[230:233], v[222:225], v[72:75]
	v_mfma_f32_16x16x32_bf16 v[64:67], v[238:241], v[222:225], v[64:67]
	v_mfma_f32_16x16x32_bf16 v[120:123], v[234:237], v[178:181], v[120:123]
	v_mfma_f32_16x16x32_bf16 v[112:115], v[242:245], v[178:181], v[112:115]
	v_mfma_f32_16x16x32_bf16 v[104:107], v[234:237], v[186:189], v[104:107]
	v_mfma_f32_16x16x32_bf16 v[96:99], v[242:245], v[186:189], v[96:99]
	v_mfma_f32_16x16x32_bf16 v[88:91], v[234:237], v[218:221], v[88:91]
	v_mfma_f32_16x16x32_bf16 v[80:83], v[242:245], v[218:221], v[80:83]
	v_mfma_f32_16x16x32_bf16 v[72:75], v[234:237], v[226:229], v[72:75]
	v_mfma_f32_16x16x32_bf16 v[64:67], v[242:245], v[226:229], v[64:67]
	s_setprio 0
	s_mov_b32 m0, s69
	v_lshl_add_u64 v[138:139], v[190:191], 0, s[70:71]
	s_barrier
	ds_read_b128 v[174:177], v145 offset:49152
	ds_read_b128 v[178:181], v145 offset:50176
	ds_read_b128 v[182:185], v145 offset:51200
	ds_read_b128 v[186:189], v145 offset:52224
	ds_read_b128 v[214:217], v145 offset:53248
	ds_read_b128 v[218:221], v145 offset:54272
	ds_read_b128 v[222:225], v145 offset:55296
	ds_read_b128 v[226:229], v145 offset:56320
	global_load_lds_dwordx4 v[138:139], off
	v_lshl_add_u64 v[138:139], v[202:203], 0, s[70:71]
	s_mov_b32 m0, s72
	s_nop 0
	global_load_lds_dwordx4 v[138:139], off
	s_barrier
	s_waitcnt lgkmcnt(0)
	s_setprio 1
	s_waitcnt lgkmcnt(0)
	v_mfma_f32_16x16x32_bf16 v[60:63], v[146:149], v[174:177], v[60:63]
	v_mfma_f32_16x16x32_bf16 v[52:55], v[166:169], v[174:177], v[52:55]
	v_mfma_f32_16x16x32_bf16 v[44:47], v[146:149], v[182:185], v[44:47]
	v_mfma_f32_16x16x32_bf16 v[36:39], v[166:169], v[182:185], v[36:39]
	v_mfma_f32_16x16x32_bf16 v[28:31], v[146:149], v[214:217], v[28:31]
	v_mfma_f32_16x16x32_bf16 v[20:23], v[166:169], v[214:217], v[20:23]
	v_mfma_f32_16x16x32_bf16 v[12:15], v[146:149], v[222:225], v[12:15]
	v_mfma_f32_16x16x32_bf16 v[4:7], v[166:169], v[222:225], v[4:7]
	v_mfma_f32_16x16x32_bf16 v[60:63], v[150:153], v[178:181], v[60:63]
	v_mfma_f32_16x16x32_bf16 v[52:55], v[170:173], v[178:181], v[52:55]
	v_mfma_f32_16x16x32_bf16 v[44:47], v[150:153], v[186:189], v[44:47]
	v_mfma_f32_16x16x32_bf16 v[36:39], v[170:173], v[186:189], v[36:39]
	v_mfma_f32_16x16x32_bf16 v[28:31], v[150:153], v[218:221], v[28:31]
	v_mfma_f32_16x16x32_bf16 v[20:23], v[170:173], v[218:221], v[20:23]
	v_mfma_f32_16x16x32_bf16 v[12:15], v[150:153], v[226:229], v[12:15]
	v_mfma_f32_16x16x32_bf16 v[4:7], v[170:173], v[226:229], v[4:7]
	s_setprio 0
	s_barrier
	s_add_u32 s62, s62, 0x40080
	s_addc_u32 s63, s63, 0
	s_add_i32 s66, s66, s31
	s_mov_b32 m0, s66
	s_nop 0
	global_load_lds_dwordx4 v158, s[62:63]
	s_add_i32 m0, s66, 0x2000
	s_nop 0
	global_load_lds_dwordx4 v132, s[62:63]
	s_waitcnt vmcnt(6)
	s_barrier
	s_setprio 1
	v_mfma_f32_16x16x32_bf16 v[56:59], v[230:233], v[174:177], v[56:59]
	v_mfma_f32_16x16x32_bf16 v[48:51], v[238:241], v[174:177], v[48:51]
	v_mfma_f32_16x16x32_bf16 v[40:43], v[230:233], v[182:185], v[40:43]
	v_mfma_f32_16x16x32_bf16 v[32:35], v[238:241], v[182:185], v[32:35]
	v_mfma_f32_16x16x32_bf16 v[24:27], v[230:233], v[214:217], v[24:27]
	v_mfma_f32_16x16x32_bf16 v[16:19], v[238:241], v[214:217], v[16:19]
	v_mfma_f32_16x16x32_bf16 v[8:11], v[230:233], v[222:225], v[8:11]
	v_mfma_f32_16x16x32_bf16 v[0:3], v[238:241], v[222:225], v[0:3]
	v_mfma_f32_16x16x32_bf16 v[56:59], v[234:237], v[178:181], v[56:59]
	v_mfma_f32_16x16x32_bf16 v[48:51], v[242:245], v[178:181], v[48:51]
	v_mfma_f32_16x16x32_bf16 v[40:43], v[234:237], v[186:189], v[40:43]
	v_mfma_f32_16x16x32_bf16 v[32:35], v[242:245], v[186:189], v[32:35]
	v_mfma_f32_16x16x32_bf16 v[24:27], v[234:237], v[218:221], v[24:27]
	v_mfma_f32_16x16x32_bf16 v[16:19], v[242:245], v[218:221], v[16:19]
	v_mfma_f32_16x16x32_bf16 v[8:11], v[234:237], v[226:229], v[8:11]
	v_mfma_f32_16x16x32_bf16 v[0:3], v[242:245], v[226:229], v[0:3]
	s_setprio 0
	s_add_i32 s75, s75, 2
	s_add_u32 s58, s58, 0x100
	s_addc_u32 s59, s59, 0
	s_add_u32 s43, s43, 0x100
	s_addc_u32 s51, s51, 0
	s_cmp_gt_u32 s75, 13
	s_barrier
	s_cbranch_scc0 .LBB0_792
